# speedup vs baseline: 1.0738x; 1.0032x over previous
; #define WAIT_V(n) asm volatile("s_waitcnt vmcnt(" #n ")" ::: "memory")
; #define BAR __builtin_amdgcn_s_barrier()
;     ...
;     f32x4 acc[2][2][4][2] = {};
;     bf16x8 At[4][2], B0[2][2], B1[2][2];
;     if (wr_s == 1) BAR;
;     if (first) WAIT_V(6); else WAIT_V(0);
;     BAR; BAR;
.LBB0_563:
	s_add_i32 s18, s56, 0x80
	v_lshl_add_u64 v[2:3], s[52:53], 0, v[136:137]
	v_mov_b32_e32 v6, s18
	v_lshl_add_u64 v[4:5], s[52:53], 0, v[138:139]
	v_mad_i64_i32 v[140:141], s[2:3], s37, v6, v[2:3]
	v_mad_i64_i32 v[142:143], s[2:3], s37, v6, v[4:5]
	v_lshl_add_u64 v[6:7], s[50:51], 0, v[136:137]
	v_mov_b32_e32 v10, s35
	v_lshl_add_u64 v[8:9], s[50:51], 0, v[138:139]
	s_add_i32 s4, s35, 0x80
	v_mad_i64_i32 v[144:145], s[2:3], s37, v10, v[6:7]
	v_mad_i64_i32 v[146:147], s[2:3], s37, v10, v[8:9]
	v_mov_b32_e32 v10, s56
	v_mad_i64_i32 v[148:149], s[2:3], s37, v10, v[2:3]
	v_mov_b32_e32 v2, s4
	v_mad_i64_i32 v[150:151], s[2:3], s37, v10, v[4:5]
	v_mad_i64_i32 v[152:153], s[2:3], s37, v2, v[6:7]
	v_mad_i64_i32 v[154:155], s[2:3], s37, v2, v[8:9]
	v_mov_b32_e32 v2, 0
	s_ashr_i32 s57, s56, 31
	s_mov_b32 s5, 0
	s_mov_b64 s[2:3], 0
	v_mov_b32_e32 v3, v2
	v_mov_b32_e32 v4, v2
	v_mov_b32_e32 v5, v2
	v_mov_b32_e32 v6, v2
	v_mov_b32_e32 v7, v2
	v_mov_b32_e32 v8, v2
	v_mov_b32_e32 v9, v2
	v_mov_b32_e32 v10, v2
	v_mov_b32_e32 v11, v2
	v_mov_b32_e32 v12, v2
	v_mov_b32_e32 v13, v2
	v_mov_b32_e32 v14, v2
	v_mov_b32_e32 v15, v2
	v_mov_b32_e32 v16, v2
	v_mov_b32_e32 v17, v2
	v_mov_b32_e32 v18, v2
	v_mov_b32_e32 v19, v2
	v_mov_b32_e32 v20, v2
	v_mov_b32_e32 v21, v2
	v_mov_b32_e32 v22, v2
	v_mov_b32_e32 v23, v2
	v_mov_b32_e32 v24, v2
	v_mov_b32_e32 v25, v2
	v_mov_b32_e32 v26, v2
	v_mov_b32_e32 v27, v2
	v_mov_b32_e32 v28, v2
	v_mov_b32_e32 v29, v2
	v_mov_b32_e32 v30, v2
	v_mov_b32_e32 v31, v2
	v_mov_b32_e32 v32, v2
	v_mov_b32_e32 v33, v2
	v_mov_b32_e32 v34, v2
	v_mov_b32_e32 v35, v2
	v_mov_b32_e32 v36, v2
	v_mov_b32_e32 v37, v2
	v_mov_b32_e32 v38, v2
	v_mov_b32_e32 v39, v2
	v_mov_b32_e32 v40, v2
	v_mov_b32_e32 v41, v2
	v_mov_b32_e32 v42, v2
	v_mov_b32_e32 v43, v2
	v_mov_b32_e32 v44, v2
	v_mov_b32_e32 v45, v2
	v_mov_b32_e32 v46, v2
	v_mov_b32_e32 v47, v2
	v_mov_b32_e32 v48, v2
	v_mov_b32_e32 v49, v2
	v_mov_b32_e32 v50, v2
	v_mov_b32_e32 v51, v2
	v_mov_b32_e32 v52, v2
	v_mov_b32_e32 v53, v2
	v_mov_b32_e32 v54, v2
	v_mov_b32_e32 v55, v2
	v_mov_b32_e32 v56, v2
	v_mov_b32_e32 v57, v2
	v_mov_b32_e32 v58, v2
	v_mov_b32_e32 v59, v2
	v_mov_b32_e32 v60, v2
	v_mov_b32_e32 v61, v2
	v_mov_b32_e32 v62, v2
	v_mov_b32_e32 v63, v2
	v_mov_b32_e32 v64, v2
	v_mov_b32_e32 v65, v2
	v_mov_b32_e32 v66, v2
	v_mov_b32_e32 v67, v2
	v_mov_b32_e32 v68, v2
	v_mov_b32_e32 v69, v2
	v_mov_b32_e32 v70, v2
	v_mov_b32_e32 v71, v2
	v_mov_b32_e32 v72, v2
	v_mov_b32_e32 v73, v2
	v_mov_b32_e32 v74, v2
	v_mov_b32_e32 v75, v2
	v_mov_b32_e32 v76, v2
	v_mov_b32_e32 v77, v2
	v_mov_b32_e32 v78, v2
	v_mov_b32_e32 v79, v2
	v_mov_b32_e32 v80, v2
	v_mov_b32_e32 v81, v2
	v_mov_b32_e32 v82, v2
	v_mov_b32_e32 v83, v2
	v_mov_b32_e32 v84, v2
	v_mov_b32_e32 v85, v2
	v_mov_b32_e32 v86, v2
	v_mov_b32_e32 v87, v2
	v_mov_b32_e32 v88, v2
	v_mov_b32_e32 v89, v2
	v_mov_b32_e32 v90, v2
	v_mov_b32_e32 v91, v2
	v_mov_b32_e32 v92, v2
	v_mov_b32_e32 v93, v2
	v_mov_b32_e32 v94, v2
	v_mov_b32_e32 v95, v2
	v_mov_b32_e32 v96, v2
	v_mov_b32_e32 v97, v2
	v_mov_b32_e32 v98, v2
	v_mov_b32_e32 v99, v2
	v_mov_b32_e32 v100, v2
	v_mov_b32_e32 v101, v2
	v_mov_b32_e32 v102, v2
	v_mov_b32_e32 v103, v2
	v_mov_b32_e32 v104, v2
	v_mov_b32_e32 v105, v2
	v_mov_b32_e32 v106, v2
	v_mov_b32_e32 v107, v2
	v_mov_b32_e32 v108, v2
	v_mov_b32_e32 v109, v2
	v_mov_b32_e32 v110, v2
	v_mov_b32_e32 v111, v2
	v_mov_b32_e32 v112, v2
	v_mov_b32_e32 v113, v2
	v_mov_b32_e32 v114, v2
	v_mov_b32_e32 v115, v2
	v_mov_b32_e32 v116, v2
	v_mov_b32_e32 v117, v2
	v_mov_b32_e32 v118, v2
	v_mov_b32_e32 v119, v2
	v_mov_b32_e32 v120, v2
	v_mov_b32_e32 v121, v2
	v_mov_b32_e32 v122, v2
	v_mov_b32_e32 v123, v2
	v_mov_b32_e32 v124, v2
	v_mov_b32_e32 v125, v2
	v_mov_b32_e32 v126, v2
	v_mov_b32_e32 v127, v2
	v_mov_b32_e32 v128, v2
	v_mov_b32_e32 v129, v2
	s_waitcnt vmcnt(0)
	s_barrier
	s_barrier

;     ...
;     if (!has_next) break;
;     first = false;
;   }
.LBB0_576:
	s_xor_b64 s[4:5], s[48:49], -1
	s_mov_b64 s[2:3], -1
	s_and_b64 vcc, exec, s[4:5]
	s_cbranch_vccz .LBB0_561
.LBB0_577:
	s_cbranch_execz .LBB0_562
	s_branch .LBB0_563

; #define GAS __attribute__((address_space(1)))
; __device__ __forceinline__ uint2 pack4(f32x4 v) { return make_uint2(pack2(v[0], v[1]), pack2(v[2], v[3])); }
; template <int MODE>
; __device__ __forceinline__ void epi_elem(char* ws, float* outp, const float* b_gate, int g0, int rl, int col, f32x4 v) {
;     ...
;   } else if (MODE == E_T || MODE == E_FF) {
;     *(GAS uint2*)((u16*)(ws + (MODE == E_T ? W_T : W_FF)) + (size_t)rl * 1024 + col) = pack4(v);
; template <int MODE>
; __device__ __forceinline__ void epi_store(char* ws, float* outp, const float* b_gate, int g0, const f32x4 (&acc)[2][2][4][2], int rbase, int cbase) {
; #pragma unroll
;   for (int ai = 0; ai < 2; ++ai)
; #pragma unroll
;     for (int bj = 0; bj < 2; ++bj)
; #pragma unroll
;       for (int m = 0; m < 4; ++m) {
; #pragma unroll
;         for (int n = 0; n < 2; ++n)
;           epi_elem<MODE>(ws, outp, b_gate, g0, rbase + ai * HALF + m * 16, cbase + bj * HALF + n * 16, acc[ai][bj][m][n]);
;         if ((m & 1) && (MODE != E_M1 && MODE != E_MG)) __builtin_amdgcn_sched_barrier(0);
;         if (m == 3 && (MODE == E_M1 || MODE == E_MG)) __builtin_amdgcn_sched_barrier(0);
;       }
.LBB0_583:
	v_readlane_b32 s2, v255, 21
	v_readlane_b32 s3, v255, 22
	s_mov_b64 s[6:7], -1
	s_and_b64 vcc, exec, s[2:3]
	s_cbranch_vccz .LBB0_620
	s_and_b64 s[4:5], s[4:5], exec
	s_cselect_b32 s8, 6, 7
	s_and_b64 s[4:5], s[30:31], exec
	v_readlane_b32 s4, v255, 29
	v_add_u32_e32 v142, s35, v1
	v_add_u32_e32 v140, s56, v184
	s_cselect_b32 s8, s8, s4
	s_ashr_i32 s4, s56, 10
	s_load_dwordx2 s[6:7], s[0:1], 0xb8
	s_load_dwordx2 s[10:11], s[0:1], 0x60
	s_load_dwordx2 s[2:3], s[0:1], 0xc0
	s_min_i32 s9, s4, 5
	v_readlane_b32 s4, v255, 14
	v_readlane_b32 s5, v255, 15
	s_and_b64 s[4:5], s[4:5], exec
	s_cselect_b32 s16, s9, s8
	s_mov_b64 s[12:13], -1
	s_mov_b64 s[8:9], 0
	s_cmp_lt_i32 s16, 4
	s_mov_b64 s[4:5], 0
	s_waitcnt lgkmcnt(0)
	s_cbranch_scc1 .LBB0_603
	s_cmp_gt_i32 s16, 5
	s_cbranch_scc0 .LBB0_597
	s_cmp_gt_i32 s16, 6
	s_cbranch_scc0 .LBB0_594
	s_cmp_gt_i32 s16, 7
	s_cbranch_scc0 .LBB0_591
	s_cmp_eq_u32 s16, 8
	s_mov_b64 s[4:5], -1
	s_cbranch_scc0 .LBB0_590
	v_bfe_u32 v141, v184, 2, 2
	v_and_b32_e32 v143, 1, v141
	v_lshrrev_b32_e32 v187, 1, v141
	v_lshlrev_b32_e32 v143, 4, v143
	v_lshl_add_u32 v143, v187, 3, v143
	v_lshlrev_b32_e32 v141, 2, v141
	v_sub_u32_e32 v143, v143, v141
	v_add_u32_e32 v143, v140, v143
	v_lshlrev_b32_e32 v141, 11, v142
	v_lshl_add_u32 v250, v143, 1, v141
	v_add_u32_e32 v251, 0x8000, v250
	v_add_u32_e32 v252, 0x10000, v250
	v_add_u32_e32 v253, 0x18000, v250
	s_add_u32 s4, s2, 0x2aec0000
	s_addc_u32 s5, s3, 0
	s_add_u32 s6, s2, 0x2af00000
	s_addc_u32 s7, s3, 0
	v_cvt_pk_bf16_f32 v144, v126, v127
	v_cvt_pk_bf16_f32 v145, v128, v129
	v_cvt_pk_bf16_f32 v146, v122, v123
	v_cvt_pk_bf16_f32 v147, v124, v125
	v_cvt_pk_bf16_f32 v148, v118, v119
	v_cvt_pk_bf16_f32 v149, v120, v121
	v_cvt_pk_bf16_f32 v150, v114, v115
	v_cvt_pk_bf16_f32 v151, v116, v117
	v_permlane16_swap_b32_e32 v144, v146
	v_permlane16_swap_b32_e32 v145, v147
	global_store_dwordx4 v250, v[144:147], s[4:5]
	v_cvt_pk_bf16_f32 v152, v110, v111
	v_cvt_pk_bf16_f32 v153, v112, v113
	v_cvt_pk_bf16_f32 v154, v106, v107
	v_cvt_pk_bf16_f32 v155, v108, v109
	v_permlane16_swap_b32_e32 v148, v150
	v_permlane16_swap_b32_e32 v149, v151
	global_store_dwordx4 v251, v[148:151], s[4:5]
	v_cvt_pk_bf16_f32 v156, v102, v103
	v_cvt_pk_bf16_f32 v157, v104, v105
	v_cvt_pk_bf16_f32 v158, v98, v99
	v_cvt_pk_bf16_f32 v159, v100, v101
	v_permlane16_swap_b32_e32 v152, v154
	v_permlane16_swap_b32_e32 v153, v155
	global_store_dwordx4 v252, v[152:155], s[4:5]
	v_cvt_pk_bf16_f32 v144, v94, v95
	v_cvt_pk_bf16_f32 v145, v96, v97
	v_cvt_pk_bf16_f32 v146, v90, v91
	v_cvt_pk_bf16_f32 v147, v92, v93
	v_permlane16_swap_b32_e32 v156, v158
	v_permlane16_swap_b32_e32 v157, v159
	global_store_dwordx4 v253, v[156:159], s[4:5]
	v_cvt_pk_bf16_f32 v148, v86, v87
	v_cvt_pk_bf16_f32 v149, v88, v89
	v_cvt_pk_bf16_f32 v150, v82, v83
	v_cvt_pk_bf16_f32 v151, v84, v85
	v_permlane16_swap_b32_e32 v144, v146
	v_permlane16_swap_b32_e32 v145, v147
	global_store_dwordx4 v250, v[144:147], s[4:5] offset:256
	v_cvt_pk_bf16_f32 v152, v78, v79
	v_cvt_pk_bf16_f32 v153, v80, v81
	v_cvt_pk_bf16_f32 v154, v74, v75
	v_cvt_pk_bf16_f32 v155, v76, v77
	v_permlane16_swap_b32_e32 v148, v150
	v_permlane16_swap_b32_e32 v149, v151
	global_store_dwordx4 v251, v[148:151], s[4:5] offset:256
	v_cvt_pk_bf16_f32 v156, v70, v71
	v_cvt_pk_bf16_f32 v157, v72, v73
	v_cvt_pk_bf16_f32 v158, v66, v67
	v_cvt_pk_bf16_f32 v159, v68, v69
	v_permlane16_swap_b32_e32 v152, v154
	v_permlane16_swap_b32_e32 v153, v155
	global_store_dwordx4 v252, v[152:155], s[4:5] offset:256
	v_cvt_pk_bf16_f32 v144, v62, v63
	v_cvt_pk_bf16_f32 v145, v64, v65
	v_cvt_pk_bf16_f32 v146, v58, v59
	v_cvt_pk_bf16_f32 v147, v60, v61
	v_permlane16_swap_b32_e32 v156, v158
	v_permlane16_swap_b32_e32 v157, v159
	global_store_dwordx4 v253, v[156:159], s[4:5] offset:256
	v_cvt_pk_bf16_f32 v148, v54, v55
	v_cvt_pk_bf16_f32 v149, v56, v57
	v_cvt_pk_bf16_f32 v150, v50, v51
	v_cvt_pk_bf16_f32 v151, v52, v53
	v_permlane16_swap_b32_e32 v144, v146
	v_permlane16_swap_b32_e32 v145, v147
	global_store_dwordx4 v250, v[144:147], s[6:7]
	v_cvt_pk_bf16_f32 v152, v46, v47
	v_cvt_pk_bf16_f32 v153, v48, v49
	v_cvt_pk_bf16_f32 v154, v42, v43
	v_cvt_pk_bf16_f32 v155, v44, v45
	v_permlane16_swap_b32_e32 v148, v150
	v_permlane16_swap_b32_e32 v149, v151
	global_store_dwordx4 v251, v[148:151], s[6:7]
	v_cvt_pk_bf16_f32 v156, v38, v39
	v_cvt_pk_bf16_f32 v157, v40, v41
	v_cvt_pk_bf16_f32 v158, v34, v35
	v_cvt_pk_bf16_f32 v159, v36, v37
	v_permlane16_swap_b32_e32 v152, v154
	v_permlane16_swap_b32_e32 v153, v155
	global_store_dwordx4 v252, v[152:155], s[6:7]
	v_cvt_pk_bf16_f32 v144, v30, v31
	v_cvt_pk_bf16_f32 v145, v32, v33
	v_cvt_pk_bf16_f32 v146, v26, v27
	v_cvt_pk_bf16_f32 v147, v28, v29
	v_permlane16_swap_b32_e32 v156, v158
	v_permlane16_swap_b32_e32 v157, v159
	global_store_dwordx4 v253, v[156:159], s[6:7]
	v_cvt_pk_bf16_f32 v148, v22, v23
	v_cvt_pk_bf16_f32 v149, v24, v25
	v_cvt_pk_bf16_f32 v150, v18, v19
	v_cvt_pk_bf16_f32 v151, v20, v21
	v_permlane16_swap_b32_e32 v144, v146
	v_permlane16_swap_b32_e32 v145, v147
	global_store_dwordx4 v250, v[144:147], s[6:7] offset:256
	v_cvt_pk_bf16_f32 v152, v14, v15
	v_cvt_pk_bf16_f32 v153, v16, v17
	v_cvt_pk_bf16_f32 v154, v10, v11
	v_cvt_pk_bf16_f32 v155, v12, v13
	v_permlane16_swap_b32_e32 v148, v150
	v_permlane16_swap_b32_e32 v149, v151
	global_store_dwordx4 v251, v[148:151], s[6:7] offset:256
	v_cvt_pk_bf16_f32 v156, v6, v7
	v_cvt_pk_bf16_f32 v157, v8, v9
	v_cvt_pk_bf16_f32 v158, v2, v3
	v_cvt_pk_bf16_f32 v159, v4, v5
	v_permlane16_swap_b32_e32 v152, v154
	v_permlane16_swap_b32_e32 v153, v155
	global_store_dwordx4 v252, v[152:155], s[6:7] offset:256
	s_nop 1
	v_permlane16_swap_b32_e32 v156, v158
	v_permlane16_swap_b32_e32 v157, v159
	global_store_dwordx4 v253, v[156:159], s[6:7] offset:256
	s_branch .LBB0_619

; #define GAS __attribute__((address_space(1)))
; __device__ __forceinline__ u16 f2bf(float f) { return (u16)(pack2(f, 0.f) & 0xffffu); }
; template <int MODE>
; __device__ __forceinline__ void epi_elem(char* ws, float* outp, const float* b_gate, int g0, int rl, int col, f32x4 v) {
;     ...
;   } else if (MODE == E_V) {
;     int lc = col & 1023;
;     u16* vt = (u16*)(ws + W_VT);
; #pragma unroll
;     for (int i = 0; i < 4; ++i) vt[(size_t)(lc + i) * MAXR + rl] = f2bf(v[i]);
;     int rg = g0 + rl;
;     float* o = rg < NPROMPT ? outp + O_VP + (size_t)rg * 1024 : outp + O_VS + (size_t)(rg - NPROMPT) * 1024;
;     __builtin_nontemporal_store(v, (GAS f32x4*)(o + lc));
.LBB0_600:
	s_andn2_b64 vcc, exec, s[12:13]
	s_cbranch_vccnz .LBB0_602
	v_ashrrev_i32_e32 v143, 31, v142
	v_lshl_add_u64 v[144:145], v[142:143], 1, s[2:3]
	s_mov_b64 s[10:11], 0x169c0000
	v_lshl_add_u64 v[174:175], v[144:145], 0, s[10:11]
	v_add_u32_e32 v141, 0x8000, v142
	s_mov_b32 s10, 0x8000
	v_add_u32_e32 v143, 0xffff8000, v142
	v_ashrrev_i32_e32 v144, 31, v141
	v_cmp_gt_i32_e32 vcc, s10, v142
	v_mov_b32_e32 v147, v0
	s_mov_b32 s10, 0x10000
	v_cndmask_b32_e32 v145, 0, v144, vcc
	v_cndmask_b32_e32 v144, v143, v141, vcc
	v_cndmask_b32_e32 v146, v205, v206, vcc
	v_lshl_add_u64 v[146:147], s[6:7], 0, v[146:147]
	v_lshlrev_b64 v[144:145], 12, v[144:145]
	v_and_b32_e32 v141, 0x3ff, v140
	v_lshl_add_u64 v[188:189], v[146:147], 0, v[144:145]
	v_mul_u32_u24_e32 v144, 0x8200, v141
	v_lshlrev_b32_e32 v144, 1, v144
	v_mov_b32_e32 v145, v0
	v_lshl_add_u64 v[144:145], v[174:175], 0, v[144:145]
	v_add_co_u32_e32 v146, vcc, s10, v144
	s_mov_b32 s11, 0x20000
	s_nop 0
	v_addc_co_u32_e32 v147, vcc, 0, v145, vcc
	v_cvt_pk_bf16_f32 v143, v126, s0
	v_add_co_u32_e32 v148, vcc, s11, v144
	global_store_short v[144:145], v143, off
	v_cvt_pk_bf16_f32 v143, v127, s0
	v_addc_co_u32_e32 v149, vcc, 0, v145, vcc
	s_mov_b32 s12, 0x30000
	global_store_short v[146:147], v143, off offset:1024
	v_cvt_pk_bf16_f32 v143, v128, s0
	v_add_co_u32_e32 v150, vcc, s12, v144
	v_lshlrev_b32_e32 v152, 2, v141
	v_mov_b32_e32 v153, v0
	v_add_u32_e32 v141, 16, v140
	global_store_short v[148:149], v143, off offset:2048
	v_cvt_pk_bf16_f32 v143, v129, s0
	v_addc_co_u32_e32 v151, vcc, 0, v145, vcc
	v_lshl_add_u64 v[154:155], v[188:189], 0, v[152:153]
	v_and_b32_e32 v141, 0x3ff, v141
	global_store_short v[150:151], v143, off offset:3072
	global_store_dwordx4 v[154:155], v[126:129], off nt
	v_mul_u32_u24_e32 v154, 0x8200, v141
	v_lshlrev_b32_e32 v154, 1, v154
	v_mov_b32_e32 v155, v0
	v_lshl_add_u64 v[154:155], v[174:175], 0, v[154:155]
	v_add_co_u32_e32 v156, vcc, s10, v154
	v_cvt_pk_bf16_f32 v143, v122, s0
	s_nop 0
	v_addc_co_u32_e32 v157, vcc, 0, v155, vcc
	v_add_co_u32_e32 v158, vcc, s11, v154
	global_store_short v[154:155], v143, off
	v_cvt_pk_bf16_f32 v143, v123, s0
	v_addc_co_u32_e32 v159, vcc, 0, v155, vcc
	global_store_short v[156:157], v143, off offset:1024
	v_cvt_pk_bf16_f32 v143, v124, s0
	v_add_co_u32_e32 v160, vcc, s12, v154
	v_lshlrev_b32_e32 v162, 2, v141
	v_mov_b32_e32 v163, v0
	global_store_short v[158:159], v143, off offset:2048
	v_cvt_pk_bf16_f32 v143, v125, s0
	v_addc_co_u32_e32 v161, vcc, 0, v155, vcc
	v_lshl_add_u64 v[164:165], v[188:189], 0, v[162:163]
	v_add_u32_e32 v141, 0x8010, v142
	s_movk_i32 s13, 0x7ff0
	global_store_short v[160:161], v143, off offset:3072
	global_store_dwordx4 v[164:165], v[122:125], off nt
	v_add_u32_e32 v143, 0xffff8010, v142
	v_ashrrev_i32_e32 v164, 31, v141
	v_cmp_gt_i32_e32 vcc, s13, v142
	v_mov_b32_e32 v167, v0
	s_nop 0
	v_cndmask_b32_e32 v165, 0, v164, vcc
	v_cndmask_b32_e32 v164, v143, v141, vcc
	v_cvt_pk_bf16_f32 v141, v118, s0
	v_cndmask_b32_e32 v166, v205, v206, vcc
	global_store_short v[144:145], v141, off offset:32
	v_cvt_pk_bf16_f32 v141, v119, s0
	v_lshl_add_u64 v[166:167], s[6:7], 0, v[166:167]
	v_lshlrev_b64 v[164:165], 12, v[164:165]
	global_store_short v[146:147], v141, off offset:1056
	v_cvt_pk_bf16_f32 v141, v120, s0
	v_lshl_add_u64 v[190:191], v[166:167], 0, v[164:165]
	global_store_short v[148:149], v141, off offset:2080
	v_cvt_pk_bf16_f32 v141, v121, s0
	global_store_short v[150:151], v141, off offset:3104
	v_lshl_add_u64 v[164:165], v[190:191], 0, v[152:153]
	v_cvt_pk_bf16_f32 v141, v114, s0
	global_store_dwordx4 v[164:165], v[118:121], off nt
	global_store_short v[154:155], v141, off offset:32
	v_cvt_pk_bf16_f32 v141, v115, s0
	global_store_short v[156:157], v141, off offset:1056
	v_cvt_pk_bf16_f32 v141, v116, s0
	global_store_short v[158:159], v141, off offset:2080
	v_cvt_pk_bf16_f32 v141, v117, s0
	v_lshl_add_u64 v[164:165], v[190:191], 0, v[162:163]
	global_store_short v[160:161], v141, off offset:3104
	global_store_dwordx4 v[164:165], v[114:117], off nt
	v_add_u32_e32 v141, 0x8020, v142
	s_movk_i32 s13, 0x7fe0
	v_add_u32_e32 v143, 0xffff8020, v142
	v_ashrrev_i32_e32 v164, 31, v141
	v_cmp_gt_i32_e32 vcc, s13, v142
	v_mov_b32_e32 v167, v0
	s_movk_i32 s13, 0x7fd0
	v_cndmask_b32_e32 v165, 0, v164, vcc
	v_cndmask_b32_e32 v164, v143, v141, vcc
	v_cvt_pk_bf16_f32 v141, v110, s0
	v_cndmask_b32_e32 v166, v205, v206, vcc
	global_store_short v[144:145], v141, off offset:64
	v_cvt_pk_bf16_f32 v141, v111, s0
	v_lshl_add_u64 v[166:167], s[6:7], 0, v[166:167]
	v_lshlrev_b64 v[164:165], 12, v[164:165]
	global_store_short v[146:147], v141, off offset:1088
	v_cvt_pk_bf16_f32 v141, v112, s0
	v_lshl_add_u64 v[192:193], v[166:167], 0, v[164:165]
	global_store_short v[148:149], v141, off offset:2112
	v_cvt_pk_bf16_f32 v141, v113, s0
	global_store_short v[150:151], v141, off offset:3136
	v_lshl_add_u64 v[164:165], v[192:193], 0, v[152:153]
	v_cvt_pk_bf16_f32 v141, v106, s0
	global_store_dwordx4 v[164:165], v[110:113], off nt
	global_store_short v[154:155], v141, off offset:64
	v_cvt_pk_bf16_f32 v141, v107, s0
	global_store_short v[156:157], v141, off offset:1088
	v_cvt_pk_bf16_f32 v141, v108, s0
	global_store_short v[158:159], v141, off offset:2112
	v_cvt_pk_bf16_f32 v141, v109, s0
	global_store_short v[160:161], v141, off offset:3136
	v_lshl_add_u64 v[164:165], v[192:193], 0, v[162:163]
	v_add_u32_e32 v141, 0x8030, v142
	global_store_dwordx4 v[164:165], v[106:109], off nt
	v_add_u32_e32 v143, 0xffff8030, v142
	v_ashrrev_i32_e32 v164, 31, v141
	v_cmp_gt_i32_e32 vcc, s13, v142
	v_mov_b32_e32 v167, v0
	s_nop 0
	v_cndmask_b32_e32 v165, 0, v164, vcc
; #define GAS __attribute__((address_space(1)))
; __device__ __forceinline__ u16 f2bf(float f) { return (u16)(pack2(f, 0.f) & 0xffffu); }
; template <int MODE>
; __device__ __forceinline__ void epi_elem(char* ws, float* outp, const float* b_gate, int g0, int rl, int col, f32x4 v) {
;     ...
;   } else if (MODE == E_V) {
;     int lc = col & 1023;
;     u16* vt = (u16*)(ws + W_VT);
; #pragma unroll
;     for (int i = 0; i < 4; ++i) vt[(size_t)(lc + i) * MAXR + rl] = f2bf(v[i]);
;     int rg = g0 + rl;
;     float* o = rg < NPROMPT ? outp + O_VP + (size_t)rg * 1024 : outp + O_VS + (size_t)(rg - NPROMPT) * 1024;
;     __builtin_nontemporal_store(v, (GAS f32x4*)(o + lc));
	v_cndmask_b32_e32 v164, v143, v141, vcc
	v_cvt_pk_bf16_f32 v141, v102, s0
	v_cndmask_b32_e32 v166, v205, v206, vcc
	global_store_short v[144:145], v141, off offset:96
	v_cvt_pk_bf16_f32 v141, v103, s0
	v_lshl_add_u64 v[166:167], s[6:7], 0, v[166:167]
	v_lshlrev_b64 v[164:165], 12, v[164:165]
	global_store_short v[146:147], v141, off offset:1120
	v_cvt_pk_bf16_f32 v141, v104, s0
	v_lshl_add_u64 v[194:195], v[166:167], 0, v[164:165]
	global_store_short v[148:149], v141, off offset:2144
	v_cvt_pk_bf16_f32 v141, v105, s0
	global_store_short v[150:151], v141, off offset:3168
	v_lshl_add_u64 v[164:165], v[194:195], 0, v[152:153]
	v_cvt_pk_bf16_f32 v141, v98, s0
	global_store_dwordx4 v[164:165], v[102:105], off nt
	global_store_short v[154:155], v141, off offset:96
	v_cvt_pk_bf16_f32 v141, v99, s0
	global_store_short v[156:157], v141, off offset:1120
	v_cvt_pk_bf16_f32 v141, v100, s0
	global_store_short v[158:159], v141, off offset:2144
	v_cvt_pk_bf16_f32 v141, v101, s0
	v_lshl_add_u64 v[164:165], v[194:195], 0, v[162:163]
	global_store_short v[160:161], v141, off offset:3168
	global_store_dwordx4 v[164:165], v[98:101], off nt
	v_add_u32_e32 v141, 0x80, v140
	v_and_b32_e32 v141, 0x3ff, v141
	v_mul_u32_u24_e32 v164, 0x8200, v141
	v_lshlrev_b32_e32 v164, 1, v164
	v_mov_b32_e32 v165, v0
	v_lshl_add_u64 v[164:165], v[174:175], 0, v[164:165]
	v_add_co_u32_e32 v166, vcc, s10, v164
	v_cvt_pk_bf16_f32 v143, v94, s0
	s_nop 0
	v_addc_co_u32_e32 v167, vcc, 0, v165, vcc
	v_add_co_u32_e32 v168, vcc, s11, v164
	global_store_short v[164:165], v143, off
	v_cvt_pk_bf16_f32 v143, v95, s0
	v_addc_co_u32_e32 v169, vcc, 0, v165, vcc
	global_store_short v[166:167], v143, off offset:1024
	v_cvt_pk_bf16_f32 v143, v96, s0
	v_add_co_u32_e32 v170, vcc, s12, v164
	v_lshlrev_b32_e32 v172, 2, v141
	v_mov_b32_e32 v173, v0
	v_add_u32_e32 v141, 0x90, v140
	global_store_short v[168:169], v143, off offset:2048
	v_cvt_pk_bf16_f32 v143, v97, s0
	v_addc_co_u32_e32 v171, vcc, 0, v165, vcc
	v_lshl_add_u64 v[176:177], v[188:189], 0, v[172:173]
	v_and_b32_e32 v141, 0x3ff, v141
	global_store_short v[170:171], v143, off offset:3072
	global_store_dwordx4 v[176:177], v[94:97], off nt
	v_mul_u32_u24_e32 v176, 0x8200, v141
	v_lshlrev_b32_e32 v176, 1, v176
	v_mov_b32_e32 v177, v0
	v_lshl_add_u64 v[174:175], v[174:175], 0, v[176:177]
	v_add_co_u32_e32 v176, vcc, s10, v174
	v_cvt_pk_bf16_f32 v143, v90, s0
	s_nop 0
	v_addc_co_u32_e32 v177, vcc, 0, v175, vcc
	v_add_co_u32_e32 v178, vcc, s11, v174
	global_store_short v[174:175], v143, off
	v_cvt_pk_bf16_f32 v143, v91, s0
	v_addc_co_u32_e32 v179, vcc, 0, v175, vcc
	global_store_short v[176:177], v143, off offset:1024
	v_cvt_pk_bf16_f32 v143, v92, s0
	v_add_co_u32_e32 v180, vcc, s12, v174
	v_lshlrev_b32_e32 v182, 2, v141
	v_mov_b32_e32 v183, v0
	global_store_short v[178:179], v143, off offset:2048
	v_cvt_pk_bf16_f32 v143, v93, s0
	v_addc_co_u32_e32 v181, vcc, 0, v175, vcc
	v_lshl_add_u64 v[188:189], v[188:189], 0, v[182:183]
	v_cvt_pk_bf16_f32 v141, v86, s0
	global_store_short v[180:181], v143, off offset:3072
	global_store_dwordx4 v[188:189], v[90:93], off nt
	global_store_short v[164:165], v141, off offset:32
	v_cvt_pk_bf16_f32 v141, v87, s0
	global_store_short v[166:167], v141, off offset:1056
	v_cvt_pk_bf16_f32 v141, v88, s0
	global_store_short v[168:169], v141, off offset:2080
	v_cvt_pk_bf16_f32 v141, v89, s0
	global_store_short v[170:171], v141, off offset:3104
	v_lshl_add_u64 v[188:189], v[190:191], 0, v[172:173]
	v_cvt_pk_bf16_f32 v141, v82, s0
	global_store_dwordx4 v[188:189], v[86:89], off nt
	global_store_short v[174:175], v141, off offset:32
	v_cvt_pk_bf16_f32 v141, v83, s0
	global_store_short v[176:177], v141, off offset:1056
	v_cvt_pk_bf16_f32 v141, v84, s0
	global_store_short v[178:179], v141, off offset:2080
	v_cvt_pk_bf16_f32 v141, v85, s0
	v_lshl_add_u64 v[188:189], v[190:191], 0, v[182:183]
	global_store_short v[180:181], v141, off offset:3104
	global_store_dwordx4 v[188:189], v[82:85], off nt
	v_cvt_pk_bf16_f32 v141, v78, s0
	global_store_short v[164:165], v141, off offset:64
	v_cvt_pk_bf16_f32 v141, v79, s0
	global_store_short v[166:167], v141, off offset:1088
	v_cvt_pk_bf16_f32 v141, v80, s0
	global_store_short v[168:169], v141, off offset:2112
	v_cvt_pk_bf16_f32 v141, v81, s0
	global_store_short v[170:171], v141, off offset:3136
	v_lshl_add_u64 v[188:189], v[192:193], 0, v[172:173]
	v_cvt_pk_bf16_f32 v141, v74, s0
	global_store_dwordx4 v[188:189], v[78:81], off nt
	global_store_short v[174:175], v141, off offset:64
	v_cvt_pk_bf16_f32 v141, v75, s0
	global_store_short v[176:177], v141, off offset:1088
	v_cvt_pk_bf16_f32 v141, v76, s0
	global_store_short v[178:179], v141, off offset:2112
	v_cvt_pk_bf16_f32 v141, v77, s0
	global_store_short v[180:181], v141, off offset:3136
	v_lshl_add_u64 v[188:189], v[192:193], 0, v[182:183]
	v_cvt_pk_bf16_f32 v141, v70, s0
	global_store_dwordx4 v[188:189], v[74:77], off nt
	global_store_short v[164:165], v141, off offset:96
	v_cvt_pk_bf16_f32 v141, v71, s0
	global_store_short v[166:167], v141, off offset:1120
	v_cvt_pk_bf16_f32 v141, v72, s0
	global_store_short v[168:169], v141, off offset:2144
	v_cvt_pk_bf16_f32 v141, v73, s0
	global_store_short v[170:171], v141, off offset:3168
	v_lshl_add_u64 v[188:189], v[194:195], 0, v[172:173]
	v_cvt_pk_bf16_f32 v141, v66, s0
	global_store_dwordx4 v[188:189], v[70:73], off nt
	global_store_short v[174:175], v141, off offset:96
	v_cvt_pk_bf16_f32 v141, v67, s0
	global_store_short v[176:177], v141, off offset:1120
	v_cvt_pk_bf16_f32 v141, v68, s0
	global_store_short v[178:179], v141, off offset:2144
	v_cvt_pk_bf16_f32 v141, v69, s0
; #define GAS __attribute__((address_space(1)))
; __device__ __forceinline__ u16 f2bf(float f) { return (u16)(pack2(f, 0.f) & 0xffffu); }
; template <int MODE>
; __device__ __forceinline__ void epi_elem(char* ws, float* outp, const float* b_gate, int g0, int rl, int col, f32x4 v) {
;     ...
;   } else if (MODE == E_V) {
;     int lc = col & 1023;
;     u16* vt = (u16*)(ws + W_VT);
; #pragma unroll
;     for (int i = 0; i < 4; ++i) vt[(size_t)(lc + i) * MAXR + rl] = f2bf(v[i]);
;     int rg = g0 + rl;
;     float* o = rg < NPROMPT ? outp + O_VP + (size_t)rg * 1024 : outp + O_VS + (size_t)(rg - NPROMPT) * 1024;
;     __builtin_nontemporal_store(v, (GAS f32x4*)(o + lc));
	v_lshl_add_u64 v[188:189], v[194:195], 0, v[182:183]
	global_store_short v[180:181], v141, off offset:3168
	global_store_dwordx4 v[188:189], v[66:69], off nt
	s_movk_i32 s10, 0x7f80
	v_add_u32_e32 v141, 0x8080, v142
	v_add_u32_e32 v143, 0xffff8080, v142
	v_cmp_gt_i32_e32 vcc, s10, v142
	v_ashrrev_i32_e32 v187, 31, v141
	v_mov_b32_e32 v191, v0
	v_cndmask_b32_e32 v188, v143, v141, vcc
	v_cvt_pk_bf16_f32 v141, v62, s0
	v_cndmask_b32_e32 v189, 0, v187, vcc
	v_cndmask_b32_e32 v190, v205, v206, vcc
	global_store_short v[144:145], v141, off offset:256
	v_cvt_pk_bf16_f32 v141, v63, s0
	v_lshl_add_u64 v[190:191], s[6:7], 0, v[190:191]
	v_lshlrev_b64 v[188:189], 12, v[188:189]
	global_store_short v[146:147], v141, off offset:1280
	v_cvt_pk_bf16_f32 v141, v64, s0
	v_lshl_add_u64 v[188:189], v[190:191], 0, v[188:189]
	global_store_short v[148:149], v141, off offset:2304
	v_cvt_pk_bf16_f32 v141, v65, s0
	global_store_short v[150:151], v141, off offset:3328
	v_lshl_add_u64 v[190:191], v[188:189], 0, v[152:153]
	v_cvt_pk_bf16_f32 v141, v58, s0
	global_store_dwordx4 v[190:191], v[62:65], off nt
	global_store_short v[154:155], v141, off offset:256
	v_cvt_pk_bf16_f32 v141, v59, s0
	global_store_short v[156:157], v141, off offset:1280
	v_cvt_pk_bf16_f32 v141, v60, s0
	global_store_short v[158:159], v141, off offset:2304
	v_cvt_pk_bf16_f32 v141, v61, s0
	s_movk_i32 s10, 0x7f70
	global_store_short v[160:161], v141, off offset:3328
	v_lshl_add_u64 v[190:191], v[188:189], 0, v[162:163]
	v_add_u32_e32 v141, 0x8090, v142
	v_add_u32_e32 v143, 0xffff8090, v142
	v_cmp_gt_i32_e32 vcc, s10, v142
	global_store_dwordx4 v[190:191], v[58:61], off nt
	v_ashrrev_i32_e32 v187, 31, v141
	v_cndmask_b32_e32 v190, v143, v141, vcc
	v_cvt_pk_bf16_f32 v141, v54, s0
	v_cndmask_b32_e32 v191, 0, v187, vcc
	v_cndmask_b32_e32 v192, v205, v206, vcc
	v_mov_b32_e32 v193, v0
	global_store_short v[144:145], v141, off offset:288
	v_cvt_pk_bf16_f32 v141, v55, s0
	v_lshl_add_u64 v[192:193], s[6:7], 0, v[192:193]
	v_lshlrev_b64 v[190:191], 12, v[190:191]
	global_store_short v[146:147], v141, off offset:1312
	v_cvt_pk_bf16_f32 v141, v56, s0
	v_lshl_add_u64 v[190:191], v[192:193], 0, v[190:191]
	global_store_short v[148:149], v141, off offset:2336
	v_cvt_pk_bf16_f32 v141, v57, s0
	global_store_short v[150:151], v141, off offset:3360
	v_lshl_add_u64 v[192:193], v[190:191], 0, v[152:153]
	v_cvt_pk_bf16_f32 v141, v50, s0
	global_store_dwordx4 v[192:193], v[54:57], off nt
	global_store_short v[154:155], v141, off offset:288
	v_cvt_pk_bf16_f32 v141, v51, s0
	global_store_short v[156:157], v141, off offset:1312
	v_cvt_pk_bf16_f32 v141, v52, s0
	global_store_short v[158:159], v141, off offset:2336
	v_cvt_pk_bf16_f32 v141, v53, s0
	v_lshl_add_u64 v[192:193], v[190:191], 0, v[162:163]
	global_store_short v[160:161], v141, off offset:3360
	global_store_dwordx4 v[192:193], v[50:53], off nt
	s_movk_i32 s10, 0x7f60
	v_add_u32_e32 v141, 0x80a0, v142
	v_add_u32_e32 v143, 0xffff80a0, v142
	v_cmp_gt_i32_e32 vcc, s10, v142
	v_ashrrev_i32_e32 v187, 31, v141
	v_mov_b32_e32 v195, v0
	v_cndmask_b32_e32 v192, v143, v141, vcc
	v_cvt_pk_bf16_f32 v141, v46, s0
	v_cndmask_b32_e32 v193, 0, v187, vcc
	v_cndmask_b32_e32 v194, v205, v206, vcc
	global_store_short v[144:145], v141, off offset:320
	v_cvt_pk_bf16_f32 v141, v47, s0
	v_lshl_add_u64 v[194:195], s[6:7], 0, v[194:195]
	v_lshlrev_b64 v[192:193], 12, v[192:193]
	global_store_short v[146:147], v141, off offset:1344
	v_cvt_pk_bf16_f32 v141, v48, s0
	v_lshl_add_u64 v[192:193], v[194:195], 0, v[192:193]
	global_store_short v[148:149], v141, off offset:2368
	v_cvt_pk_bf16_f32 v141, v49, s0
	global_store_short v[150:151], v141, off offset:3392
	v_lshl_add_u64 v[194:195], v[192:193], 0, v[152:153]
	v_cvt_pk_bf16_f32 v141, v42, s0
	global_store_dwordx4 v[194:195], v[46:49], off nt
	global_store_short v[154:155], v141, off offset:320
	v_cvt_pk_bf16_f32 v141, v43, s0
	global_store_short v[156:157], v141, off offset:1344
	v_cvt_pk_bf16_f32 v141, v44, s0
	global_store_short v[158:159], v141, off offset:2368
	v_cvt_pk_bf16_f32 v141, v45, s0
	s_movk_i32 s10, 0x7f50
	global_store_short v[160:161], v141, off offset:3392
	v_lshl_add_u64 v[194:195], v[192:193], 0, v[162:163]
	v_add_u32_e32 v141, 0x80b0, v142
	v_add_u32_e32 v143, 0xffff80b0, v142
	v_cmp_gt_i32_e32 vcc, s10, v142
	global_store_dwordx4 v[194:195], v[42:45], off nt
	v_ashrrev_i32_e32 v187, 31, v141
	v_cndmask_b32_e32 v194, v143, v141, vcc
	v_cvt_pk_bf16_f32 v141, v38, s0
	v_cndmask_b32_e32 v195, 0, v187, vcc
	v_cndmask_b32_e32 v196, v205, v206, vcc
	v_mov_b32_e32 v197, v0
; #define GAS __attribute__((address_space(1)))
; __device__ __forceinline__ u16 f2bf(float f) { return (u16)(pack2(f, 0.f) & 0xffffu); }
; template <int MODE>
; __device__ __forceinline__ void epi_elem(char* ws, float* outp, const float* b_gate, int g0, int rl, int col, f32x4 v) {
;     ...
;   } else if (MODE == E_V) {
;     int lc = col & 1023;
;     u16* vt = (u16*)(ws + W_VT);
; #pragma unroll
;     for (int i = 0; i < 4; ++i) vt[(size_t)(lc + i) * MAXR + rl] = f2bf(v[i]);
;     int rg = g0 + rl;
;     float* o = rg < NPROMPT ? outp + O_VP + (size_t)rg * 1024 : outp + O_VS + (size_t)(rg - NPROMPT) * 1024;
;     __builtin_nontemporal_store(v, (GAS f32x4*)(o + lc));
; template <int MODE>
; __device__ __forceinline__ void epi_store(char* ws, float* outp, const float* b_gate, int g0, const f32x4 (&acc)[2][2][4][2], int rbase, int cbase) {
; #pragma unroll
;   for (int ai = 0; ai < 2; ++ai)
; #pragma unroll
;     for (int bj = 0; bj < 2; ++bj)
; #pragma unroll
;       for (int m = 0; m < 4; ++m) {
; #pragma unroll
;         for (int n = 0; n < 2; ++n)
;           epi_elem<MODE>(ws, outp, b_gate, g0, rbase + ai * HALF + m * 16, cbase + bj * HALF + n * 16, acc[ai][bj][m][n]);
;         if ((m & 1) && (MODE != E_M1 && MODE != E_MG)) __builtin_amdgcn_sched_barrier(0);
;         if (m == 3 && (MODE == E_M1 || MODE == E_MG)) __builtin_amdgcn_sched_barrier(0);
;       }
	global_store_short v[144:145], v141, off offset:352
	v_cvt_pk_bf16_f32 v141, v39, s0
	v_lshl_add_u64 v[196:197], s[6:7], 0, v[196:197]
	v_lshlrev_b64 v[194:195], 12, v[194:195]
	global_store_short v[146:147], v141, off offset:1376
	v_cvt_pk_bf16_f32 v141, v40, s0
	v_lshl_add_u64 v[194:195], v[196:197], 0, v[194:195]
	global_store_short v[148:149], v141, off offset:2400
	v_cvt_pk_bf16_f32 v141, v41, s0
	global_store_short v[150:151], v141, off offset:3424
	v_lshl_add_u64 v[144:145], v[194:195], 0, v[152:153]
	v_cvt_pk_bf16_f32 v141, v34, s0
	global_store_dwordx4 v[144:145], v[38:41], off nt
	global_store_short v[154:155], v141, off offset:352
	v_cvt_pk_bf16_f32 v141, v35, s0
	global_store_short v[156:157], v141, off offset:1376
	v_cvt_pk_bf16_f32 v141, v36, s0
	global_store_short v[158:159], v141, off offset:2400
	v_cvt_pk_bf16_f32 v141, v37, s0
	v_lshl_add_u64 v[144:145], v[194:195], 0, v[162:163]
	global_store_short v[160:161], v141, off offset:3424
	global_store_dwordx4 v[144:145], v[34:37], off nt
	v_cvt_pk_bf16_f32 v141, v30, s0
	global_store_short v[164:165], v141, off offset:256
	v_cvt_pk_bf16_f32 v141, v31, s0
	global_store_short v[166:167], v141, off offset:1280
	v_cvt_pk_bf16_f32 v141, v32, s0
	global_store_short v[168:169], v141, off offset:2304
	v_cvt_pk_bf16_f32 v141, v33, s0
	global_store_short v[170:171], v141, off offset:3328
	v_lshl_add_u64 v[144:145], v[188:189], 0, v[172:173]
	v_cvt_pk_bf16_f32 v141, v26, s0
	global_store_dwordx4 v[144:145], v[30:33], off nt
	global_store_short v[174:175], v141, off offset:256
	v_cvt_pk_bf16_f32 v141, v27, s0
	global_store_short v[176:177], v141, off offset:1280
	v_cvt_pk_bf16_f32 v141, v28, s0
	global_store_short v[178:179], v141, off offset:2304
	v_cvt_pk_bf16_f32 v141, v29, s0
	global_store_short v[180:181], v141, off offset:3328
	v_lshl_add_u64 v[144:145], v[188:189], 0, v[182:183]
	v_cvt_pk_bf16_f32 v141, v22, s0
	global_store_dwordx4 v[144:145], v[26:29], off nt
	global_store_short v[164:165], v141, off offset:288
	v_cvt_pk_bf16_f32 v141, v23, s0
	global_store_short v[166:167], v141, off offset:1312
	v_cvt_pk_bf16_f32 v141, v24, s0
	global_store_short v[168:169], v141, off offset:2336
	v_cvt_pk_bf16_f32 v141, v25, s0
	global_store_short v[170:171], v141, off offset:3360
	v_lshl_add_u64 v[144:145], v[190:191], 0, v[172:173]
	v_cvt_pk_bf16_f32 v141, v18, s0
	global_store_dwordx4 v[144:145], v[22:25], off nt
	global_store_short v[174:175], v141, off offset:288
	v_cvt_pk_bf16_f32 v141, v19, s0
	global_store_short v[176:177], v141, off offset:1312
	v_cvt_pk_bf16_f32 v141, v20, s0
	global_store_short v[178:179], v141, off offset:2336
	v_cvt_pk_bf16_f32 v141, v21, s0
	v_lshl_add_u64 v[144:145], v[190:191], 0, v[182:183]
	global_store_short v[180:181], v141, off offset:3360
	global_store_dwordx4 v[144:145], v[18:21], off nt
	v_cvt_pk_bf16_f32 v141, v14, s0
	global_store_short v[164:165], v141, off offset:320
	v_cvt_pk_bf16_f32 v141, v15, s0
	global_store_short v[166:167], v141, off offset:1344
	v_cvt_pk_bf16_f32 v141, v16, s0
	global_store_short v[168:169], v141, off offset:2368
	v_cvt_pk_bf16_f32 v141, v17, s0
	global_store_short v[170:171], v141, off offset:3392
	v_lshl_add_u64 v[144:145], v[192:193], 0, v[172:173]
	v_cvt_pk_bf16_f32 v141, v10, s0
	global_store_dwordx4 v[144:145], v[14:17], off nt
	global_store_short v[174:175], v141, off offset:320
	v_cvt_pk_bf16_f32 v141, v11, s0
	global_store_short v[176:177], v141, off offset:1344
	v_cvt_pk_bf16_f32 v141, v12, s0
	global_store_short v[178:179], v141, off offset:2368
	v_cvt_pk_bf16_f32 v141, v13, s0
	global_store_short v[180:181], v141, off offset:3392
	v_lshl_add_u64 v[144:145], v[192:193], 0, v[182:183]
	v_cvt_pk_bf16_f32 v141, v6, s0
	global_store_dwordx4 v[144:145], v[10:13], off nt
	global_store_short v[164:165], v141, off offset:352
	v_cvt_pk_bf16_f32 v141, v7, s0
	global_store_short v[166:167], v141, off offset:1376
	v_cvt_pk_bf16_f32 v141, v8, s0
	global_store_short v[168:169], v141, off offset:2400
	v_cvt_pk_bf16_f32 v141, v9, s0
	global_store_short v[170:171], v141, off offset:3424
	v_lshl_add_u64 v[144:145], v[194:195], 0, v[172:173]
	v_cvt_pk_bf16_f32 v141, v2, s0
	global_store_dwordx4 v[144:145], v[6:9], off nt
	global_store_short v[174:175], v141, off offset:352
	v_cvt_pk_bf16_f32 v141, v3, s0
	global_store_short v[176:177], v141, off offset:1376
	v_cvt_pk_bf16_f32 v141, v4, s0
	global_store_short v[178:179], v141, off offset:2400
	v_cvt_pk_bf16_f32 v141, v5, s0
	v_lshl_add_u64 v[144:145], v[194:195], 0, v[182:183]
	global_store_short v[180:181], v141, off offset:3424
	global_store_dwordx4 v[144:145], v[2:5], off nt

; #define GAS __attribute__((address_space(1)))
; __device__ __forceinline__ uint2 pack4(f32x4 v) { return make_uint2(pack2(v[0], v[1]), pack2(v[2], v[3])); }
; template <int MODE>
; __device__ __forceinline__ void epi_elem(char* ws, float* outp, const float* b_gate, int g0, int rl, int col, f32x4 v) {
;     ...
;   } else if (MODE == E_K) {
;     int lc = col & 1023;
;     *(GAS uint2*)((u16*)(ws + W_K) + (size_t)rl * 1024 + lc) = pack4(v);
;     int rg = g0 + rl;
;     float* o = rg < NPROMPT ? outp + O_KP + (size_t)rg * 1024 : outp + O_KS + (size_t)(rg - NPROMPT) * 1024;
;     __builtin_nontemporal_store(v, (GAS f32x4*)(o + lc));
; template <int MODE>
; __device__ __forceinline__ void epi_store(char* ws, float* outp, const float* b_gate, int g0, const f32x4 (&acc)[2][2][4][2], int rbase, int cbase) {
; #pragma unroll
;   for (int ai = 0; ai < 2; ++ai)
; #pragma unroll
;     for (int bj = 0; bj < 2; ++bj)
; #pragma unroll
;       for (int m = 0; m < 4; ++m) {
; #pragma unroll
;         for (int n = 0; n < 2; ++n)
;           epi_elem<MODE>(ws, outp, b_gate, g0, rbase + ai * HALF + m * 16, cbase + bj * HALF + n * 16, acc[ai][bj][m][n]);
;         if ((m & 1) && (MODE != E_M1 && MODE != E_MG)) __builtin_amdgcn_sched_barrier(0);
;         if (m == 3 && (MODE == E_M1 || MODE == E_MG)) __builtin_amdgcn_sched_barrier(0);
;       }
.LBB0_603:
	s_and_b64 vcc, exec, s[12:13]
	s_cbranch_vccz .LBB0_615
	s_cmp_gt_i32 s16, 1
	s_mov_b64 s[8:9], -1
	s_cbranch_scc0 .LBB0_610
	s_cmp_gt_i32 s16, 2
	s_cbranch_scc0 .LBB0_607
	s_mov_b32 s16, 0x8000
	v_bfe_u32 v141, v184, 2, 2
	v_and_b32_e32 v143, 1, v141
	v_lshrrev_b32_e32 v187, 1, v141
	v_lshlrev_b32_e32 v143, 4, v143
	v_lshl_add_u32 v143, v187, 3, v143
	v_lshlrev_b32_e32 v141, 2, v141
	v_sub_u32_e32 v143, v143, v141
	v_add_u32_e32 v143, v140, v143
	v_and_b32_e32 v143, 0x3ff, v143
	v_lshlrev_b32_e32 v141, 11, v142
	v_lshl_add_u32 v250, v143, 1, v141
	v_add_u32_e32 v251, 0x8000, v250
	v_add_u32_e32 v252, 0x10000, v250
	v_add_u32_e32 v253, 0x18000, v250
	s_add_u32 s4, s2, 0x128c0000
	s_addc_u32 s5, s3, 0
	s_add_u32 s8, s2, 0x12900000
	s_addc_u32 s9, s3, 0
	s_add_u32 s14, s6, 0x80000
	s_addc_u32 s15, s7, 0
	s_mov_b32 s17, 0x10000
	v_add_u32_e32 v187, s16, v142
	v_and_b32_e32 v141, 0x3ff, v140
	v_cmp_gt_i32_e32 vcc, s17, v187
	v_add_u32_e32 v188, 0xffff0000, v187
	v_lshlrev_b32_e32 v141, 2, v141
	s_nop 0
	v_cndmask_b32_e32 v187, v188, v187, vcc
	v_cndmask_b32_e32 v188, v207, v208, vcc
	v_lshl_add_u32 v187, v187, 12, v188
	v_add_u32_e32 v246, v187, v141
	v_add_u32_e32 v247, 0x10000, v246
	v_add_u32_e32 v248, 0x20000, v246
	v_add_u32_e32 v249, 0x30000, v246
	v_cvt_pk_bf16_f32 v144, v126, v127
	v_cvt_pk_bf16_f32 v145, v128, v129
	v_cvt_pk_bf16_f32 v146, v122, v123
	v_cvt_pk_bf16_f32 v147, v124, v125
	global_store_dwordx4 v246, v[126:129], s[6:7] nt
	global_store_dwordx4 v246, v[122:125], s[6:7] offset:64 nt
	v_cvt_pk_bf16_f32 v148, v118, v119
	v_cvt_pk_bf16_f32 v149, v120, v121
	v_cvt_pk_bf16_f32 v150, v114, v115
	v_cvt_pk_bf16_f32 v151, v116, v117
	global_store_dwordx4 v247, v[118:121], s[6:7] nt
	global_store_dwordx4 v247, v[114:117], s[6:7] offset:64 nt
	v_permlane16_swap_b32_e32 v144, v146
	v_permlane16_swap_b32_e32 v145, v147
	global_store_dwordx4 v250, v[144:147], s[4:5]
	v_cvt_pk_bf16_f32 v152, v110, v111
	v_cvt_pk_bf16_f32 v153, v112, v113
	v_cvt_pk_bf16_f32 v154, v106, v107
	v_cvt_pk_bf16_f32 v155, v108, v109
	global_store_dwordx4 v248, v[110:113], s[6:7] nt
	global_store_dwordx4 v248, v[106:109], s[6:7] offset:64 nt
	v_permlane16_swap_b32_e32 v148, v150
	v_permlane16_swap_b32_e32 v149, v151
	global_store_dwordx4 v251, v[148:151], s[4:5]
	v_cvt_pk_bf16_f32 v156, v102, v103
	v_cvt_pk_bf16_f32 v157, v104, v105
	v_cvt_pk_bf16_f32 v158, v98, v99
	v_cvt_pk_bf16_f32 v159, v100, v101
	global_store_dwordx4 v249, v[102:105], s[6:7] nt
	global_store_dwordx4 v249, v[98:101], s[6:7] offset:64 nt
	v_permlane16_swap_b32_e32 v152, v154
	v_permlane16_swap_b32_e32 v153, v155
	global_store_dwordx4 v252, v[152:155], s[4:5]
	v_cvt_pk_bf16_f32 v144, v94, v95
	v_cvt_pk_bf16_f32 v145, v96, v97
	v_cvt_pk_bf16_f32 v146, v90, v91
	v_cvt_pk_bf16_f32 v147, v92, v93
	global_store_dwordx4 v246, v[94:97], s[6:7] offset:512 nt
	global_store_dwordx4 v246, v[90:93], s[6:7] offset:576 nt
	v_permlane16_swap_b32_e32 v156, v158
	v_permlane16_swap_b32_e32 v157, v159
	global_store_dwordx4 v253, v[156:159], s[4:5]
	v_cvt_pk_bf16_f32 v148, v86, v87
	v_cvt_pk_bf16_f32 v149, v88, v89
	v_cvt_pk_bf16_f32 v150, v82, v83
	v_cvt_pk_bf16_f32 v151, v84, v85
	global_store_dwordx4 v247, v[86:89], s[6:7] offset:512 nt
	global_store_dwordx4 v247, v[82:85], s[6:7] offset:576 nt
	v_permlane16_swap_b32_e32 v144, v146
	v_permlane16_swap_b32_e32 v145, v147
	global_store_dwordx4 v250, v[144:147], s[4:5] offset:256
	v_cvt_pk_bf16_f32 v152, v78, v79
	v_cvt_pk_bf16_f32 v153, v80, v81
	v_cvt_pk_bf16_f32 v154, v74, v75
	v_cvt_pk_bf16_f32 v155, v76, v77
	global_store_dwordx4 v248, v[78:81], s[6:7] offset:512 nt
	global_store_dwordx4 v248, v[74:77], s[6:7] offset:576 nt
; #define GAS __attribute__((address_space(1)))
; __device__ __forceinline__ uint2 pack4(f32x4 v) { return make_uint2(pack2(v[0], v[1]), pack2(v[2], v[3])); }
; template <int MODE>
; __device__ __forceinline__ void epi_elem(char* ws, float* outp, const float* b_gate, int g0, int rl, int col, f32x4 v) {
;     ...
;   } else if (MODE == E_K) {
;     int lc = col & 1023;
;     *(GAS uint2*)((u16*)(ws + W_K) + (size_t)rl * 1024 + lc) = pack4(v);
;     int rg = g0 + rl;
;     float* o = rg < NPROMPT ? outp + O_KP + (size_t)rg * 1024 : outp + O_KS + (size_t)(rg - NPROMPT) * 1024;
;     __builtin_nontemporal_store(v, (GAS f32x4*)(o + lc));
; template <int MODE>
; __device__ __forceinline__ void epi_store(char* ws, float* outp, const float* b_gate, int g0, const f32x4 (&acc)[2][2][4][2], int rbase, int cbase) {
; #pragma unroll
;   for (int ai = 0; ai < 2; ++ai)
; #pragma unroll
;     for (int bj = 0; bj < 2; ++bj)
; #pragma unroll
;       for (int m = 0; m < 4; ++m) {
; #pragma unroll
;         for (int n = 0; n < 2; ++n)
;           epi_elem<MODE>(ws, outp, b_gate, g0, rbase + ai * HALF + m * 16, cbase + bj * HALF + n * 16, acc[ai][bj][m][n]);
;         if ((m & 1) && (MODE != E_M1 && MODE != E_MG)) __builtin_amdgcn_sched_barrier(0);
;         if (m == 3 && (MODE == E_M1 || MODE == E_MG)) __builtin_amdgcn_sched_barrier(0);
;       }
	v_permlane16_swap_b32_e32 v148, v150
	v_permlane16_swap_b32_e32 v149, v151
	global_store_dwordx4 v251, v[148:151], s[4:5] offset:256
	v_cvt_pk_bf16_f32 v156, v70, v71
	v_cvt_pk_bf16_f32 v157, v72, v73
	v_cvt_pk_bf16_f32 v158, v66, v67
	v_cvt_pk_bf16_f32 v159, v68, v69
	global_store_dwordx4 v249, v[70:73], s[6:7] offset:512 nt
	global_store_dwordx4 v249, v[66:69], s[6:7] offset:576 nt
	v_permlane16_swap_b32_e32 v152, v154
	v_permlane16_swap_b32_e32 v153, v155
	global_store_dwordx4 v252, v[152:155], s[4:5] offset:256
	v_cvt_pk_bf16_f32 v144, v62, v63
	v_cvt_pk_bf16_f32 v145, v64, v65
	v_cvt_pk_bf16_f32 v146, v58, v59
	v_cvt_pk_bf16_f32 v147, v60, v61
	global_store_dwordx4 v246, v[62:65], s[14:15] nt
	global_store_dwordx4 v246, v[58:61], s[14:15] offset:64 nt
	v_permlane16_swap_b32_e32 v156, v158
	v_permlane16_swap_b32_e32 v157, v159
	global_store_dwordx4 v253, v[156:159], s[4:5] offset:256
	v_cvt_pk_bf16_f32 v148, v54, v55
	v_cvt_pk_bf16_f32 v149, v56, v57
	v_cvt_pk_bf16_f32 v150, v50, v51
	v_cvt_pk_bf16_f32 v151, v52, v53
	global_store_dwordx4 v247, v[54:57], s[14:15] nt
	global_store_dwordx4 v247, v[50:53], s[14:15] offset:64 nt
	v_permlane16_swap_b32_e32 v144, v146
	v_permlane16_swap_b32_e32 v145, v147
	global_store_dwordx4 v250, v[144:147], s[8:9]
	v_cvt_pk_bf16_f32 v152, v46, v47
	v_cvt_pk_bf16_f32 v153, v48, v49
	v_cvt_pk_bf16_f32 v154, v42, v43
	v_cvt_pk_bf16_f32 v155, v44, v45
	global_store_dwordx4 v248, v[46:49], s[14:15] nt
	global_store_dwordx4 v248, v[42:45], s[14:15] offset:64 nt
	v_permlane16_swap_b32_e32 v148, v150
	v_permlane16_swap_b32_e32 v149, v151
	global_store_dwordx4 v251, v[148:151], s[8:9]
	v_cvt_pk_bf16_f32 v156, v38, v39
	v_cvt_pk_bf16_f32 v157, v40, v41
	v_cvt_pk_bf16_f32 v158, v34, v35
	v_cvt_pk_bf16_f32 v159, v36, v37
	global_store_dwordx4 v249, v[38:41], s[14:15] nt
	global_store_dwordx4 v249, v[34:37], s[14:15] offset:64 nt
	v_permlane16_swap_b32_e32 v152, v154
	v_permlane16_swap_b32_e32 v153, v155
	global_store_dwordx4 v252, v[152:155], s[8:9]
	v_cvt_pk_bf16_f32 v144, v30, v31
	v_cvt_pk_bf16_f32 v145, v32, v33
	v_cvt_pk_bf16_f32 v146, v26, v27
	v_cvt_pk_bf16_f32 v147, v28, v29
	global_store_dwordx4 v246, v[30:33], s[14:15] offset:512 nt
	global_store_dwordx4 v246, v[26:29], s[14:15] offset:576 nt
	v_permlane16_swap_b32_e32 v156, v158
	v_permlane16_swap_b32_e32 v157, v159
	global_store_dwordx4 v253, v[156:159], s[8:9]
	v_cvt_pk_bf16_f32 v148, v22, v23
	v_cvt_pk_bf16_f32 v149, v24, v25
	v_cvt_pk_bf16_f32 v150, v18, v19
	v_cvt_pk_bf16_f32 v151, v20, v21
	global_store_dwordx4 v247, v[22:25], s[14:15] offset:512 nt
	global_store_dwordx4 v247, v[18:21], s[14:15] offset:576 nt
	v_permlane16_swap_b32_e32 v144, v146
	v_permlane16_swap_b32_e32 v145, v147
	global_store_dwordx4 v250, v[144:147], s[8:9] offset:256
	v_cvt_pk_bf16_f32 v152, v14, v15
	v_cvt_pk_bf16_f32 v153, v16, v17
	v_cvt_pk_bf16_f32 v154, v10, v11
	v_cvt_pk_bf16_f32 v155, v12, v13
	global_store_dwordx4 v248, v[14:17], s[14:15] offset:512 nt
	global_store_dwordx4 v248, v[10:13], s[14:15] offset:576 nt
	v_permlane16_swap_b32_e32 v148, v150
	v_permlane16_swap_b32_e32 v149, v151
	global_store_dwordx4 v251, v[148:151], s[8:9] offset:256
	v_cvt_pk_bf16_f32 v156, v6, v7
	v_cvt_pk_bf16_f32 v157, v8, v9
	v_cvt_pk_bf16_f32 v158, v2, v3
	v_cvt_pk_bf16_f32 v159, v4, v5
	global_store_dwordx4 v249, v[6:9], s[14:15] offset:512 nt
	global_store_dwordx4 v249, v[2:5], s[14:15] offset:576 nt
	v_permlane16_swap_b32_e32 v152, v154
	v_permlane16_swap_b32_e32 v153, v155
	global_store_dwordx4 v252, v[152:155], s[8:9] offset:256
	s_nop 1
	v_permlane16_swap_b32_e32 v156, v158
	v_permlane16_swap_b32_e32 v157, v159
	global_store_dwordx4 v253, v[156:159], s[8:9] offset:256
	s_branch .LBB0_619

; #define GAS __attribute__((address_space(1)))
; __device__ __forceinline__ uint2 pack4(f32x4 v) { return make_uint2(pack2(v[0], v[1]), pack2(v[2], v[3])); }
; __device__ __forceinline__ float gelu_f(float x) {
;   const float c1 = -1.5957691216057308f * 1.4426950408889634f, c2 = c1 * 0.044715f;
;   float u = x * __builtin_fmaf(x * x, c2, c1);
;   return x * __builtin_amdgcn_rcpf(1.0f + __builtin_amdgcn_exp2f(u));
; }
; template <int MODE>
; __device__ __forceinline__ void epi_elem(char* ws, float* outp, const float* b_gate, int g0, int rl, int col, f32x4 v) {
;   if (MODE == E_U || MODE == E_GV) {
;     int lc = col & 1023;
;     f32x4 o; for (int i = 0; i < 4; ++i) o[i] = gelu_f(v[i]);
;     u16* dst = (u16*)(ws + (MODE == E_U ? W_U : W_GV));
;     *(GAS uint2*)(dst + (size_t)rl * 1024 + lc) = pack4(o);
.LBB0_617:
	s_andn2_b64 vcc, exec, s[8:9]
	s_cbranch_vccnz .LBB0_619
	v_bfe_u32 v141, v184, 2, 2
	v_and_b32_e32 v143, 1, v141
	v_lshrrev_b32_e32 v187, 1, v141
	v_lshlrev_b32_e32 v143, 4, v143
	v_lshl_add_u32 v143, v187, 3, v143
	v_lshlrev_b32_e32 v141, 2, v141
	v_sub_u32_e32 v143, v143, v141
	v_add_u32_e32 v143, v140, v143
	v_and_b32_e32 v143, 0x3ff, v143
	v_lshlrev_b32_e32 v141, 11, v142
	v_lshl_add_u32 v250, v143, 1, v141
	v_add_u32_e32 v251, 0x8000, v250
	v_add_u32_e32 v252, 0x10000, v250
	v_add_u32_e32 v253, 0x18000, v250
	s_add_u32 s4, s2, 0x65c0000
	s_addc_u32 s5, s3, 0
	s_add_u32 s6, s2, 0x6600000
	s_addc_u32 s7, s3, 0
	s_mov_b32 s18, 0xbdd2d3e7
	v_mul_f32_e32 v160, v126, v126
	v_mul_f32_e32 v161, v127, v127
	v_mul_f32_e32 v162, v128, v128
	v_mul_f32_e32 v163, v129, v129
	v_mul_f32_e32 v164, v122, v122
	v_mul_f32_e32 v165, v123, v123
	v_mul_f32_e32 v166, v124, v124
	v_mul_f32_e32 v167, v125, v125
	v_fma_f32 v160, v160, s18, v198
	v_fma_f32 v161, v161, s18, v198
	v_fma_f32 v162, v162, s18, v198
	v_fma_f32 v163, v163, s18, v198
	v_fma_f32 v164, v164, s18, v198
	v_fma_f32 v165, v165, s18, v198
	v_fma_f32 v166, v166, s18, v198
	v_fma_f32 v167, v167, s18, v198
	v_mul_f32_e32 v160, v126, v160
	v_mul_f32_e32 v161, v127, v161
	v_mul_f32_e32 v162, v128, v162
	v_mul_f32_e32 v163, v129, v163
	v_mul_f32_e32 v164, v122, v164
	v_mul_f32_e32 v165, v123, v165
	v_mul_f32_e32 v166, v124, v166
	v_mul_f32_e32 v167, v125, v167
	v_exp_f32_e32 v160, v160
	v_exp_f32_e32 v161, v161
	v_exp_f32_e32 v162, v162
	v_exp_f32_e32 v163, v163
	v_exp_f32_e32 v164, v164
	v_exp_f32_e32 v165, v165
	v_exp_f32_e32 v166, v166
	v_exp_f32_e32 v167, v167
	v_add_f32_e32 v160, 1.0, v160
	v_add_f32_e32 v161, 1.0, v161
	v_add_f32_e32 v162, 1.0, v162
	v_add_f32_e32 v163, 1.0, v163
	v_add_f32_e32 v164, 1.0, v164
	v_add_f32_e32 v165, 1.0, v165
	v_add_f32_e32 v166, 1.0, v166
	v_add_f32_e32 v167, 1.0, v167
	v_rcp_f32_e32 v160, v160
	v_rcp_f32_e32 v161, v161
	v_rcp_f32_e32 v162, v162
	v_rcp_f32_e32 v163, v163
	v_rcp_f32_e32 v164, v164
	v_rcp_f32_e32 v165, v165
	v_rcp_f32_e32 v166, v166
	v_rcp_f32_e32 v167, v167
	v_mul_f32_e32 v160, v126, v160
	v_mul_f32_e32 v161, v127, v161
	v_mul_f32_e32 v162, v128, v162
	v_mul_f32_e32 v163, v129, v163
	v_mul_f32_e32 v164, v122, v164
	v_mul_f32_e32 v165, v123, v165
	v_mul_f32_e32 v166, v124, v166
	v_mul_f32_e32 v167, v125, v167
	v_cvt_pk_bf16_f32 v144, v160, v161
	v_cvt_pk_bf16_f32 v145, v162, v163
	v_cvt_pk_bf16_f32 v146, v164, v165
	v_cvt_pk_bf16_f32 v147, v166, v167
	v_mul_f32_e32 v168, v118, v118
	v_mul_f32_e32 v169, v119, v119
	v_mul_f32_e32 v170, v120, v120
	v_mul_f32_e32 v171, v121, v121
	v_mul_f32_e32 v172, v114, v114
	v_mul_f32_e32 v173, v115, v115
	v_mul_f32_e32 v174, v116, v116
	v_mul_f32_e32 v175, v117, v117
	v_fma_f32 v168, v168, s18, v198
	v_fma_f32 v169, v169, s18, v198
	v_fma_f32 v170, v170, s18, v198
	v_fma_f32 v171, v171, s18, v198
	v_fma_f32 v172, v172, s18, v198
	v_fma_f32 v173, v173, s18, v198
	v_fma_f32 v174, v174, s18, v198
	v_fma_f32 v175, v175, s18, v198
	v_mul_f32_e32 v168, v118, v168
	v_mul_f32_e32 v169, v119, v169
	v_mul_f32_e32 v170, v120, v170
	v_mul_f32_e32 v171, v121, v171
	v_mul_f32_e32 v172, v114, v172
	v_mul_f32_e32 v173, v115, v173
	v_mul_f32_e32 v174, v116, v174
	v_mul_f32_e32 v175, v117, v175
	v_exp_f32_e32 v168, v168
	v_exp_f32_e32 v169, v169
	v_exp_f32_e32 v170, v170
	v_exp_f32_e32 v171, v171
	v_exp_f32_e32 v172, v172
	v_exp_f32_e32 v173, v173
	v_exp_f32_e32 v174, v174
	v_exp_f32_e32 v175, v175
	v_add_f32_e32 v168, 1.0, v168
	v_add_f32_e32 v169, 1.0, v169
	v_add_f32_e32 v170, 1.0, v170
	v_add_f32_e32 v171, 1.0, v171
	v_add_f32_e32 v172, 1.0, v172
	v_add_f32_e32 v173, 1.0, v173
	v_add_f32_e32 v174, 1.0, v174
	v_add_f32_e32 v175, 1.0, v175
	v_rcp_f32_e32 v168, v168
	v_rcp_f32_e32 v169, v169
	v_rcp_f32_e32 v170, v170
	v_rcp_f32_e32 v171, v171
	v_rcp_f32_e32 v172, v172
	v_rcp_f32_e32 v173, v173
	v_rcp_f32_e32 v174, v174
	v_rcp_f32_e32 v175, v175
	v_mul_f32_e32 v168, v118, v168
	v_mul_f32_e32 v169, v119, v169
	v_mul_f32_e32 v170, v120, v170
	v_mul_f32_e32 v171, v121, v171
	v_mul_f32_e32 v172, v114, v172
	v_mul_f32_e32 v173, v115, v173
	v_mul_f32_e32 v174, v116, v174
	v_mul_f32_e32 v175, v117, v175
	v_cvt_pk_bf16_f32 v148, v168, v169
	v_cvt_pk_bf16_f32 v149, v170, v171
	v_cvt_pk_bf16_f32 v150, v172, v173
	v_cvt_pk_bf16_f32 v151, v174, v175
	v_permlane16_swap_b32_e32 v144, v146
	v_permlane16_swap_b32_e32 v145, v147
	global_store_dwordx4 v250, v[144:147], s[4:5]
	v_mul_f32_e32 v160, v110, v110
	v_mul_f32_e32 v161, v111, v111
	v_mul_f32_e32 v162, v112, v112
	v_mul_f32_e32 v163, v113, v113
	v_mul_f32_e32 v164, v106, v106
	v_mul_f32_e32 v165, v107, v107
	v_mul_f32_e32 v166, v108, v108
	v_mul_f32_e32 v167, v109, v109
	v_fma_f32 v160, v160, s18, v198
	v_fma_f32 v161, v161, s18, v198
	v_fma_f32 v162, v162, s18, v198
	v_fma_f32 v163, v163, s18, v198
	v_fma_f32 v164, v164, s18, v198
	v_fma_f32 v165, v165, s18, v198
	v_fma_f32 v166, v166, s18, v198
	v_fma_f32 v167, v167, s18, v198
	v_mul_f32_e32 v160, v110, v160
	v_mul_f32_e32 v161, v111, v161
	v_mul_f32_e32 v162, v112, v162
	v_mul_f32_e32 v163, v113, v163
	v_mul_f32_e32 v164, v106, v164
	v_mul_f32_e32 v165, v107, v165
	v_mul_f32_e32 v166, v108, v166
	v_mul_f32_e32 v167, v109, v167
	v_exp_f32_e32 v160, v160
	v_exp_f32_e32 v161, v161
	v_exp_f32_e32 v162, v162
	v_exp_f32_e32 v163, v163
	v_exp_f32_e32 v164, v164
	v_exp_f32_e32 v165, v165
	v_exp_f32_e32 v166, v166
	v_exp_f32_e32 v167, v167
	v_add_f32_e32 v160, 1.0, v160
	v_add_f32_e32 v161, 1.0, v161
	v_add_f32_e32 v162, 1.0, v162
	v_add_f32_e32 v163, 1.0, v163
	v_add_f32_e32 v164, 1.0, v164
	v_add_f32_e32 v165, 1.0, v165
; #define GAS __attribute__((address_space(1)))
; __device__ __forceinline__ uint2 pack4(f32x4 v) { return make_uint2(pack2(v[0], v[1]), pack2(v[2], v[3])); }
; __device__ __forceinline__ float gelu_f(float x) {
;   const float c1 = -1.5957691216057308f * 1.4426950408889634f, c2 = c1 * 0.044715f;
;   float u = x * __builtin_fmaf(x * x, c2, c1);
;   return x * __builtin_amdgcn_rcpf(1.0f + __builtin_amdgcn_exp2f(u));
; }
; template <int MODE>
; __device__ __forceinline__ void epi_elem(char* ws, float* outp, const float* b_gate, int g0, int rl, int col, f32x4 v) {
;   if (MODE == E_U || MODE == E_GV) {
;     int lc = col & 1023;
;     f32x4 o; for (int i = 0; i < 4; ++i) o[i] = gelu_f(v[i]);
;     u16* dst = (u16*)(ws + (MODE == E_U ? W_U : W_GV));
;     *(GAS uint2*)(dst + (size_t)rl * 1024 + lc) = pack4(o);
	v_add_f32_e32 v166, 1.0, v166
	v_add_f32_e32 v167, 1.0, v167
	v_rcp_f32_e32 v160, v160
	v_rcp_f32_e32 v161, v161
	v_rcp_f32_e32 v162, v162
	v_rcp_f32_e32 v163, v163
	v_rcp_f32_e32 v164, v164
	v_rcp_f32_e32 v165, v165
	v_rcp_f32_e32 v166, v166
	v_rcp_f32_e32 v167, v167
	v_mul_f32_e32 v160, v110, v160
	v_mul_f32_e32 v161, v111, v161
	v_mul_f32_e32 v162, v112, v162
	v_mul_f32_e32 v163, v113, v163
	v_mul_f32_e32 v164, v106, v164
	v_mul_f32_e32 v165, v107, v165
	v_mul_f32_e32 v166, v108, v166
	v_mul_f32_e32 v167, v109, v167
	v_cvt_pk_bf16_f32 v152, v160, v161
	v_cvt_pk_bf16_f32 v153, v162, v163
	v_cvt_pk_bf16_f32 v154, v164, v165
	v_cvt_pk_bf16_f32 v155, v166, v167
	v_permlane16_swap_b32_e32 v148, v150
	v_permlane16_swap_b32_e32 v149, v151
	global_store_dwordx4 v251, v[148:151], s[4:5]
	v_mul_f32_e32 v168, v102, v102
	v_mul_f32_e32 v169, v103, v103
	v_mul_f32_e32 v170, v104, v104
	v_mul_f32_e32 v171, v105, v105
	v_mul_f32_e32 v172, v98, v98
	v_mul_f32_e32 v173, v99, v99
	v_mul_f32_e32 v174, v100, v100
	v_mul_f32_e32 v175, v101, v101
	v_fma_f32 v168, v168, s18, v198
	v_fma_f32 v169, v169, s18, v198
	v_fma_f32 v170, v170, s18, v198
	v_fma_f32 v171, v171, s18, v198
	v_fma_f32 v172, v172, s18, v198
	v_fma_f32 v173, v173, s18, v198
	v_fma_f32 v174, v174, s18, v198
	v_fma_f32 v175, v175, s18, v198
	v_mul_f32_e32 v168, v102, v168
	v_mul_f32_e32 v169, v103, v169
	v_mul_f32_e32 v170, v104, v170
	v_mul_f32_e32 v171, v105, v171
	v_mul_f32_e32 v172, v98, v172
	v_mul_f32_e32 v173, v99, v173
	v_mul_f32_e32 v174, v100, v174
	v_mul_f32_e32 v175, v101, v175
	v_exp_f32_e32 v168, v168
	v_exp_f32_e32 v169, v169
	v_exp_f32_e32 v170, v170
	v_exp_f32_e32 v171, v171
	v_exp_f32_e32 v172, v172
	v_exp_f32_e32 v173, v173
	v_exp_f32_e32 v174, v174
	v_exp_f32_e32 v175, v175
	v_add_f32_e32 v168, 1.0, v168
	v_add_f32_e32 v169, 1.0, v169
	v_add_f32_e32 v170, 1.0, v170
	v_add_f32_e32 v171, 1.0, v171
	v_add_f32_e32 v172, 1.0, v172
	v_add_f32_e32 v173, 1.0, v173
	v_add_f32_e32 v174, 1.0, v174
	v_add_f32_e32 v175, 1.0, v175
	v_rcp_f32_e32 v168, v168
	v_rcp_f32_e32 v169, v169
	v_rcp_f32_e32 v170, v170
	v_rcp_f32_e32 v171, v171
	v_rcp_f32_e32 v172, v172
	v_rcp_f32_e32 v173, v173
	v_rcp_f32_e32 v174, v174
	v_rcp_f32_e32 v175, v175
	v_mul_f32_e32 v168, v102, v168
	v_mul_f32_e32 v169, v103, v169
	v_mul_f32_e32 v170, v104, v170
	v_mul_f32_e32 v171, v105, v171
	v_mul_f32_e32 v172, v98, v172
	v_mul_f32_e32 v173, v99, v173
	v_mul_f32_e32 v174, v100, v174
	v_mul_f32_e32 v175, v101, v175
	v_cvt_pk_bf16_f32 v156, v168, v169
	v_cvt_pk_bf16_f32 v157, v170, v171
	v_cvt_pk_bf16_f32 v158, v172, v173
	v_cvt_pk_bf16_f32 v159, v174, v175
	v_permlane16_swap_b32_e32 v152, v154
	v_permlane16_swap_b32_e32 v153, v155
	global_store_dwordx4 v252, v[152:155], s[4:5]
	v_mul_f32_e32 v160, v94, v94
	v_mul_f32_e32 v161, v95, v95
	v_mul_f32_e32 v162, v96, v96
	v_mul_f32_e32 v163, v97, v97
	v_mul_f32_e32 v164, v90, v90
	v_mul_f32_e32 v165, v91, v91
	v_mul_f32_e32 v166, v92, v92
	v_mul_f32_e32 v167, v93, v93
	v_fma_f32 v160, v160, s18, v198
	v_fma_f32 v161, v161, s18, v198
	v_fma_f32 v162, v162, s18, v198
	v_fma_f32 v163, v163, s18, v198
	v_fma_f32 v164, v164, s18, v198
	v_fma_f32 v165, v165, s18, v198
	v_fma_f32 v166, v166, s18, v198
	v_fma_f32 v167, v167, s18, v198
	v_mul_f32_e32 v160, v94, v160
	v_mul_f32_e32 v161, v95, v161
	v_mul_f32_e32 v162, v96, v162
	v_mul_f32_e32 v163, v97, v163
	v_mul_f32_e32 v164, v90, v164
	v_mul_f32_e32 v165, v91, v165
	v_mul_f32_e32 v166, v92, v166
	v_mul_f32_e32 v167, v93, v167
	v_exp_f32_e32 v160, v160
	v_exp_f32_e32 v161, v161
	v_exp_f32_e32 v162, v162
	v_exp_f32_e32 v163, v163
	v_exp_f32_e32 v164, v164
	v_exp_f32_e32 v165, v165
	v_exp_f32_e32 v166, v166
	v_exp_f32_e32 v167, v167
	v_add_f32_e32 v160, 1.0, v160
	v_add_f32_e32 v161, 1.0, v161
	v_add_f32_e32 v162, 1.0, v162
	v_add_f32_e32 v163, 1.0, v163
	v_add_f32_e32 v164, 1.0, v164
	v_add_f32_e32 v165, 1.0, v165
	v_add_f32_e32 v166, 1.0, v166
	v_add_f32_e32 v167, 1.0, v167
	v_rcp_f32_e32 v160, v160
	v_rcp_f32_e32 v161, v161
	v_rcp_f32_e32 v162, v162
	v_rcp_f32_e32 v163, v163
	v_rcp_f32_e32 v164, v164
	v_rcp_f32_e32 v165, v165
	v_rcp_f32_e32 v166, v166
	v_rcp_f32_e32 v167, v167
	v_mul_f32_e32 v160, v94, v160
	v_mul_f32_e32 v161, v95, v161
	v_mul_f32_e32 v162, v96, v162
	v_mul_f32_e32 v163, v97, v163
	v_mul_f32_e32 v164, v90, v164
	v_mul_f32_e32 v165, v91, v165
	v_mul_f32_e32 v166, v92, v166
	v_mul_f32_e32 v167, v93, v167
	v_cvt_pk_bf16_f32 v144, v160, v161
	v_cvt_pk_bf16_f32 v145, v162, v163
	v_cvt_pk_bf16_f32 v146, v164, v165
	v_cvt_pk_bf16_f32 v147, v166, v167
	v_permlane16_swap_b32_e32 v156, v158
	v_permlane16_swap_b32_e32 v157, v159
	global_store_dwordx4 v253, v[156:159], s[4:5]
	v_mul_f32_e32 v168, v86, v86
	v_mul_f32_e32 v169, v87, v87
	v_mul_f32_e32 v170, v88, v88
	v_mul_f32_e32 v171, v89, v89
	v_mul_f32_e32 v172, v82, v82
	v_mul_f32_e32 v173, v83, v83
	v_mul_f32_e32 v174, v84, v84
	v_mul_f32_e32 v175, v85, v85
	v_fma_f32 v168, v168, s18, v198
	v_fma_f32 v169, v169, s18, v198
	v_fma_f32 v170, v170, s18, v198
	v_fma_f32 v171, v171, s18, v198
	v_fma_f32 v172, v172, s18, v198
	v_fma_f32 v173, v173, s18, v198
	v_fma_f32 v174, v174, s18, v198
	v_fma_f32 v175, v175, s18, v198
	v_mul_f32_e32 v168, v86, v168
	v_mul_f32_e32 v169, v87, v169
	v_mul_f32_e32 v170, v88, v170
	v_mul_f32_e32 v171, v89, v171
	v_mul_f32_e32 v172, v82, v172
	v_mul_f32_e32 v173, v83, v173
	v_mul_f32_e32 v174, v84, v174
	v_mul_f32_e32 v175, v85, v175
	v_exp_f32_e32 v168, v168
	v_exp_f32_e32 v169, v169
	v_exp_f32_e32 v170, v170
	v_exp_f32_e32 v171, v171
	v_exp_f32_e32 v172, v172
	v_exp_f32_e32 v173, v173
	v_exp_f32_e32 v174, v174
	v_exp_f32_e32 v175, v175
; #define GAS __attribute__((address_space(1)))
; __device__ __forceinline__ uint2 pack4(f32x4 v) { return make_uint2(pack2(v[0], v[1]), pack2(v[2], v[3])); }
; __device__ __forceinline__ float gelu_f(float x) {
;   const float c1 = -1.5957691216057308f * 1.4426950408889634f, c2 = c1 * 0.044715f;
;   float u = x * __builtin_fmaf(x * x, c2, c1);
;   return x * __builtin_amdgcn_rcpf(1.0f + __builtin_amdgcn_exp2f(u));
; }
; template <int MODE>
; __device__ __forceinline__ void epi_elem(char* ws, float* outp, const float* b_gate, int g0, int rl, int col, f32x4 v) {
;   if (MODE == E_U || MODE == E_GV) {
;     int lc = col & 1023;
;     f32x4 o; for (int i = 0; i < 4; ++i) o[i] = gelu_f(v[i]);
;     u16* dst = (u16*)(ws + (MODE == E_U ? W_U : W_GV));
;     *(GAS uint2*)(dst + (size_t)rl * 1024 + lc) = pack4(o);
	v_add_f32_e32 v168, 1.0, v168
	v_add_f32_e32 v169, 1.0, v169
	v_add_f32_e32 v170, 1.0, v170
	v_add_f32_e32 v171, 1.0, v171
	v_add_f32_e32 v172, 1.0, v172
	v_add_f32_e32 v173, 1.0, v173
	v_add_f32_e32 v174, 1.0, v174
	v_add_f32_e32 v175, 1.0, v175
	v_rcp_f32_e32 v168, v168
	v_rcp_f32_e32 v169, v169
	v_rcp_f32_e32 v170, v170
	v_rcp_f32_e32 v171, v171
	v_rcp_f32_e32 v172, v172
	v_rcp_f32_e32 v173, v173
	v_rcp_f32_e32 v174, v174
	v_rcp_f32_e32 v175, v175
	v_mul_f32_e32 v168, v86, v168
	v_mul_f32_e32 v169, v87, v169
	v_mul_f32_e32 v170, v88, v170
	v_mul_f32_e32 v171, v89, v171
	v_mul_f32_e32 v172, v82, v172
	v_mul_f32_e32 v173, v83, v173
	v_mul_f32_e32 v174, v84, v174
	v_mul_f32_e32 v175, v85, v175
	v_cvt_pk_bf16_f32 v148, v168, v169
	v_cvt_pk_bf16_f32 v149, v170, v171
	v_cvt_pk_bf16_f32 v150, v172, v173
	v_cvt_pk_bf16_f32 v151, v174, v175
	v_permlane16_swap_b32_e32 v144, v146
	v_permlane16_swap_b32_e32 v145, v147
	global_store_dwordx4 v250, v[144:147], s[4:5] offset:256
	v_mul_f32_e32 v160, v78, v78
	v_mul_f32_e32 v161, v79, v79
	v_mul_f32_e32 v162, v80, v80
	v_mul_f32_e32 v163, v81, v81
	v_mul_f32_e32 v164, v74, v74
	v_mul_f32_e32 v165, v75, v75
	v_mul_f32_e32 v166, v76, v76
	v_mul_f32_e32 v167, v77, v77
	v_fma_f32 v160, v160, s18, v198
	v_fma_f32 v161, v161, s18, v198
	v_fma_f32 v162, v162, s18, v198
	v_fma_f32 v163, v163, s18, v198
	v_fma_f32 v164, v164, s18, v198
	v_fma_f32 v165, v165, s18, v198
	v_fma_f32 v166, v166, s18, v198
	v_fma_f32 v167, v167, s18, v198
	v_mul_f32_e32 v160, v78, v160
	v_mul_f32_e32 v161, v79, v161
	v_mul_f32_e32 v162, v80, v162
	v_mul_f32_e32 v163, v81, v163
	v_mul_f32_e32 v164, v74, v164
	v_mul_f32_e32 v165, v75, v165
	v_mul_f32_e32 v166, v76, v166
	v_mul_f32_e32 v167, v77, v167
	v_exp_f32_e32 v160, v160
	v_exp_f32_e32 v161, v161
	v_exp_f32_e32 v162, v162
	v_exp_f32_e32 v163, v163
	v_exp_f32_e32 v164, v164
	v_exp_f32_e32 v165, v165
	v_exp_f32_e32 v166, v166
	v_exp_f32_e32 v167, v167
	v_add_f32_e32 v160, 1.0, v160
	v_add_f32_e32 v161, 1.0, v161
	v_add_f32_e32 v162, 1.0, v162
	v_add_f32_e32 v163, 1.0, v163
	v_add_f32_e32 v164, 1.0, v164
	v_add_f32_e32 v165, 1.0, v165
	v_add_f32_e32 v166, 1.0, v166
	v_add_f32_e32 v167, 1.0, v167
	v_rcp_f32_e32 v160, v160
	v_rcp_f32_e32 v161, v161
	v_rcp_f32_e32 v162, v162
	v_rcp_f32_e32 v163, v163
	v_rcp_f32_e32 v164, v164
	v_rcp_f32_e32 v165, v165
	v_rcp_f32_e32 v166, v166
	v_rcp_f32_e32 v167, v167
	v_mul_f32_e32 v160, v78, v160
	v_mul_f32_e32 v161, v79, v161
	v_mul_f32_e32 v162, v80, v162
	v_mul_f32_e32 v163, v81, v163
	v_mul_f32_e32 v164, v74, v164
	v_mul_f32_e32 v165, v75, v165
	v_mul_f32_e32 v166, v76, v166
	v_mul_f32_e32 v167, v77, v167
	v_cvt_pk_bf16_f32 v152, v160, v161
	v_cvt_pk_bf16_f32 v153, v162, v163
	v_cvt_pk_bf16_f32 v154, v164, v165
	v_cvt_pk_bf16_f32 v155, v166, v167
	v_permlane16_swap_b32_e32 v148, v150
	v_permlane16_swap_b32_e32 v149, v151
	global_store_dwordx4 v251, v[148:151], s[4:5] offset:256
	v_mul_f32_e32 v168, v70, v70
	v_mul_f32_e32 v169, v71, v71
	v_mul_f32_e32 v170, v72, v72
	v_mul_f32_e32 v171, v73, v73
	v_mul_f32_e32 v172, v66, v66
	v_mul_f32_e32 v173, v67, v67
	v_mul_f32_e32 v174, v68, v68
	v_mul_f32_e32 v175, v69, v69
	v_fma_f32 v168, v168, s18, v198
	v_fma_f32 v169, v169, s18, v198
	v_fma_f32 v170, v170, s18, v198
	v_fma_f32 v171, v171, s18, v198
	v_fma_f32 v172, v172, s18, v198
	v_fma_f32 v173, v173, s18, v198
	v_fma_f32 v174, v174, s18, v198
	v_fma_f32 v175, v175, s18, v198
	v_mul_f32_e32 v168, v70, v168
	v_mul_f32_e32 v169, v71, v169
	v_mul_f32_e32 v170, v72, v170
	v_mul_f32_e32 v171, v73, v171
	v_mul_f32_e32 v172, v66, v172
	v_mul_f32_e32 v173, v67, v173
	v_mul_f32_e32 v174, v68, v174
	v_mul_f32_e32 v175, v69, v175
	v_exp_f32_e32 v168, v168
	v_exp_f32_e32 v169, v169
	v_exp_f32_e32 v170, v170
	v_exp_f32_e32 v171, v171
	v_exp_f32_e32 v172, v172
	v_exp_f32_e32 v173, v173
	v_exp_f32_e32 v174, v174
	v_exp_f32_e32 v175, v175
	v_add_f32_e32 v168, 1.0, v168
	v_add_f32_e32 v169, 1.0, v169
	v_add_f32_e32 v170, 1.0, v170
	v_add_f32_e32 v171, 1.0, v171
	v_add_f32_e32 v172, 1.0, v172
	v_add_f32_e32 v173, 1.0, v173
	v_add_f32_e32 v174, 1.0, v174
	v_add_f32_e32 v175, 1.0, v175
	v_rcp_f32_e32 v168, v168
	v_rcp_f32_e32 v169, v169
	v_rcp_f32_e32 v170, v170
	v_rcp_f32_e32 v171, v171
	v_rcp_f32_e32 v172, v172
	v_rcp_f32_e32 v173, v173
	v_rcp_f32_e32 v174, v174
	v_rcp_f32_e32 v175, v175
	v_mul_f32_e32 v168, v70, v168
	v_mul_f32_e32 v169, v71, v169
	v_mul_f32_e32 v170, v72, v170
	v_mul_f32_e32 v171, v73, v171
	v_mul_f32_e32 v172, v66, v172
	v_mul_f32_e32 v173, v67, v173
	v_mul_f32_e32 v174, v68, v174
	v_mul_f32_e32 v175, v69, v175
	v_cvt_pk_bf16_f32 v156, v168, v169
	v_cvt_pk_bf16_f32 v157, v170, v171
	v_cvt_pk_bf16_f32 v158, v172, v173
	v_cvt_pk_bf16_f32 v159, v174, v175
	v_permlane16_swap_b32_e32 v152, v154
	v_permlane16_swap_b32_e32 v153, v155
	global_store_dwordx4 v252, v[152:155], s[4:5] offset:256
	v_mul_f32_e32 v160, v62, v62
	v_mul_f32_e32 v161, v63, v63
	v_mul_f32_e32 v162, v64, v64
	v_mul_f32_e32 v163, v65, v65
	v_mul_f32_e32 v164, v58, v58
	v_mul_f32_e32 v165, v59, v59
	v_mul_f32_e32 v166, v60, v60
	v_mul_f32_e32 v167, v61, v61
	v_fma_f32 v160, v160, s18, v198
	v_fma_f32 v161, v161, s18, v198
	v_fma_f32 v162, v162, s18, v198
	v_fma_f32 v163, v163, s18, v198
	v_fma_f32 v164, v164, s18, v198
	v_fma_f32 v165, v165, s18, v198
	v_fma_f32 v166, v166, s18, v198
	v_fma_f32 v167, v167, s18, v198
	v_mul_f32_e32 v160, v62, v160
	v_mul_f32_e32 v161, v63, v161
	v_mul_f32_e32 v162, v64, v162
	v_mul_f32_e32 v163, v65, v163
	v_mul_f32_e32 v164, v58, v164
	v_mul_f32_e32 v165, v59, v165
	v_mul_f32_e32 v166, v60, v166
	v_mul_f32_e32 v167, v61, v167
	v_exp_f32_e32 v160, v160
; #define GAS __attribute__((address_space(1)))
; __device__ __forceinline__ uint2 pack4(f32x4 v) { return make_uint2(pack2(v[0], v[1]), pack2(v[2], v[3])); }
; __device__ __forceinline__ float gelu_f(float x) {
;   const float c1 = -1.5957691216057308f * 1.4426950408889634f, c2 = c1 * 0.044715f;
;   float u = x * __builtin_fmaf(x * x, c2, c1);
;   return x * __builtin_amdgcn_rcpf(1.0f + __builtin_amdgcn_exp2f(u));
; }
; template <int MODE>
; __device__ __forceinline__ void epi_elem(char* ws, float* outp, const float* b_gate, int g0, int rl, int col, f32x4 v) {
;   if (MODE == E_U || MODE == E_GV) {
;     int lc = col & 1023;
;     f32x4 o; for (int i = 0; i < 4; ++i) o[i] = gelu_f(v[i]);
;     u16* dst = (u16*)(ws + (MODE == E_U ? W_U : W_GV));
;     *(GAS uint2*)(dst + (size_t)rl * 1024 + lc) = pack4(o);
	v_exp_f32_e32 v161, v161
	v_exp_f32_e32 v162, v162
	v_exp_f32_e32 v163, v163
	v_exp_f32_e32 v164, v164
	v_exp_f32_e32 v165, v165
	v_exp_f32_e32 v166, v166
	v_exp_f32_e32 v167, v167
	v_add_f32_e32 v160, 1.0, v160
	v_add_f32_e32 v161, 1.0, v161
	v_add_f32_e32 v162, 1.0, v162
	v_add_f32_e32 v163, 1.0, v163
	v_add_f32_e32 v164, 1.0, v164
	v_add_f32_e32 v165, 1.0, v165
	v_add_f32_e32 v166, 1.0, v166
	v_add_f32_e32 v167, 1.0, v167
	v_rcp_f32_e32 v160, v160
	v_rcp_f32_e32 v161, v161
	v_rcp_f32_e32 v162, v162
	v_rcp_f32_e32 v163, v163
	v_rcp_f32_e32 v164, v164
	v_rcp_f32_e32 v165, v165
	v_rcp_f32_e32 v166, v166
	v_rcp_f32_e32 v167, v167
	v_mul_f32_e32 v160, v62, v160
	v_mul_f32_e32 v161, v63, v161
	v_mul_f32_e32 v162, v64, v162
	v_mul_f32_e32 v163, v65, v163
	v_mul_f32_e32 v164, v58, v164
	v_mul_f32_e32 v165, v59, v165
	v_mul_f32_e32 v166, v60, v166
	v_mul_f32_e32 v167, v61, v167
	v_cvt_pk_bf16_f32 v144, v160, v161
	v_cvt_pk_bf16_f32 v145, v162, v163
	v_cvt_pk_bf16_f32 v146, v164, v165
	v_cvt_pk_bf16_f32 v147, v166, v167
	v_permlane16_swap_b32_e32 v156, v158
	v_permlane16_swap_b32_e32 v157, v159
	global_store_dwordx4 v253, v[156:159], s[4:5] offset:256
	v_mul_f32_e32 v168, v54, v54
	v_mul_f32_e32 v169, v55, v55
	v_mul_f32_e32 v170, v56, v56
	v_mul_f32_e32 v171, v57, v57
	v_mul_f32_e32 v172, v50, v50
	v_mul_f32_e32 v173, v51, v51
	v_mul_f32_e32 v174, v52, v52
	v_mul_f32_e32 v175, v53, v53
	v_fma_f32 v168, v168, s18, v198
	v_fma_f32 v169, v169, s18, v198
	v_fma_f32 v170, v170, s18, v198
	v_fma_f32 v171, v171, s18, v198
	v_fma_f32 v172, v172, s18, v198
	v_fma_f32 v173, v173, s18, v198
	v_fma_f32 v174, v174, s18, v198
	v_fma_f32 v175, v175, s18, v198
	v_mul_f32_e32 v168, v54, v168
	v_mul_f32_e32 v169, v55, v169
	v_mul_f32_e32 v170, v56, v170
	v_mul_f32_e32 v171, v57, v171
	v_mul_f32_e32 v172, v50, v172
	v_mul_f32_e32 v173, v51, v173
	v_mul_f32_e32 v174, v52, v174
	v_mul_f32_e32 v175, v53, v175
	v_exp_f32_e32 v168, v168
	v_exp_f32_e32 v169, v169
	v_exp_f32_e32 v170, v170
	v_exp_f32_e32 v171, v171
	v_exp_f32_e32 v172, v172
	v_exp_f32_e32 v173, v173
	v_exp_f32_e32 v174, v174
	v_exp_f32_e32 v175, v175
	v_add_f32_e32 v168, 1.0, v168
	v_add_f32_e32 v169, 1.0, v169
	v_add_f32_e32 v170, 1.0, v170
	v_add_f32_e32 v171, 1.0, v171
	v_add_f32_e32 v172, 1.0, v172
	v_add_f32_e32 v173, 1.0, v173
	v_add_f32_e32 v174, 1.0, v174
	v_add_f32_e32 v175, 1.0, v175
	v_rcp_f32_e32 v168, v168
	v_rcp_f32_e32 v169, v169
	v_rcp_f32_e32 v170, v170
	v_rcp_f32_e32 v171, v171
	v_rcp_f32_e32 v172, v172
	v_rcp_f32_e32 v173, v173
	v_rcp_f32_e32 v174, v174
	v_rcp_f32_e32 v175, v175
	v_mul_f32_e32 v168, v54, v168
	v_mul_f32_e32 v169, v55, v169
	v_mul_f32_e32 v170, v56, v170
	v_mul_f32_e32 v171, v57, v171
	v_mul_f32_e32 v172, v50, v172
	v_mul_f32_e32 v173, v51, v173
	v_mul_f32_e32 v174, v52, v174
	v_mul_f32_e32 v175, v53, v175
	v_cvt_pk_bf16_f32 v148, v168, v169
	v_cvt_pk_bf16_f32 v149, v170, v171
	v_cvt_pk_bf16_f32 v150, v172, v173
	v_cvt_pk_bf16_f32 v151, v174, v175
	v_permlane16_swap_b32_e32 v144, v146
	v_permlane16_swap_b32_e32 v145, v147
	global_store_dwordx4 v250, v[144:147], s[6:7]
	v_mul_f32_e32 v160, v46, v46
	v_mul_f32_e32 v161, v47, v47
	v_mul_f32_e32 v162, v48, v48
	v_mul_f32_e32 v163, v49, v49
	v_mul_f32_e32 v164, v42, v42
	v_mul_f32_e32 v165, v43, v43
	v_mul_f32_e32 v166, v44, v44
	v_mul_f32_e32 v167, v45, v45
	v_fma_f32 v160, v160, s18, v198
	v_fma_f32 v161, v161, s18, v198
	v_fma_f32 v162, v162, s18, v198
	v_fma_f32 v163, v163, s18, v198
	v_fma_f32 v164, v164, s18, v198
	v_fma_f32 v165, v165, s18, v198
	v_fma_f32 v166, v166, s18, v198
	v_fma_f32 v167, v167, s18, v198
	v_mul_f32_e32 v160, v46, v160
	v_mul_f32_e32 v161, v47, v161
	v_mul_f32_e32 v162, v48, v162
	v_mul_f32_e32 v163, v49, v163
	v_mul_f32_e32 v164, v42, v164
	v_mul_f32_e32 v165, v43, v165
	v_mul_f32_e32 v166, v44, v166
	v_mul_f32_e32 v167, v45, v167
	v_exp_f32_e32 v160, v160
	v_exp_f32_e32 v161, v161
	v_exp_f32_e32 v162, v162
	v_exp_f32_e32 v163, v163
	v_exp_f32_e32 v164, v164
	v_exp_f32_e32 v165, v165
	v_exp_f32_e32 v166, v166
	v_exp_f32_e32 v167, v167
	v_add_f32_e32 v160, 1.0, v160
	v_add_f32_e32 v161, 1.0, v161
	v_add_f32_e32 v162, 1.0, v162
	v_add_f32_e32 v163, 1.0, v163
	v_add_f32_e32 v164, 1.0, v164
	v_add_f32_e32 v165, 1.0, v165
	v_add_f32_e32 v166, 1.0, v166
	v_add_f32_e32 v167, 1.0, v167
	v_rcp_f32_e32 v160, v160
	v_rcp_f32_e32 v161, v161
	v_rcp_f32_e32 v162, v162
	v_rcp_f32_e32 v163, v163
	v_rcp_f32_e32 v164, v164
	v_rcp_f32_e32 v165, v165
	v_rcp_f32_e32 v166, v166
	v_rcp_f32_e32 v167, v167
	v_mul_f32_e32 v160, v46, v160
	v_mul_f32_e32 v161, v47, v161
	v_mul_f32_e32 v162, v48, v162
	v_mul_f32_e32 v163, v49, v163
	v_mul_f32_e32 v164, v42, v164
	v_mul_f32_e32 v165, v43, v165
	v_mul_f32_e32 v166, v44, v166
	v_mul_f32_e32 v167, v45, v167
	v_cvt_pk_bf16_f32 v152, v160, v161
	v_cvt_pk_bf16_f32 v153, v162, v163
	v_cvt_pk_bf16_f32 v154, v164, v165
	v_cvt_pk_bf16_f32 v155, v166, v167
	v_permlane16_swap_b32_e32 v148, v150
	v_permlane16_swap_b32_e32 v149, v151
	global_store_dwordx4 v251, v[148:151], s[6:7]
	v_mul_f32_e32 v168, v38, v38
	v_mul_f32_e32 v169, v39, v39
	v_mul_f32_e32 v170, v40, v40
	v_mul_f32_e32 v171, v41, v41
	v_mul_f32_e32 v172, v34, v34
	v_mul_f32_e32 v173, v35, v35
	v_mul_f32_e32 v174, v36, v36
	v_mul_f32_e32 v175, v37, v37
	v_fma_f32 v168, v168, s18, v198
	v_fma_f32 v169, v169, s18, v198
	v_fma_f32 v170, v170, s18, v198
	v_fma_f32 v171, v171, s18, v198
	v_fma_f32 v172, v172, s18, v198
	v_fma_f32 v173, v173, s18, v198
	v_fma_f32 v174, v174, s18, v198
	v_fma_f32 v175, v175, s18, v198
	v_mul_f32_e32 v168, v38, v168
	v_mul_f32_e32 v169, v39, v169
	v_mul_f32_e32 v170, v40, v170
	v_mul_f32_e32 v171, v41, v171
; #define GAS __attribute__((address_space(1)))
; __device__ __forceinline__ uint2 pack4(f32x4 v) { return make_uint2(pack2(v[0], v[1]), pack2(v[2], v[3])); }
; __device__ __forceinline__ float gelu_f(float x) {
;   const float c1 = -1.5957691216057308f * 1.4426950408889634f, c2 = c1 * 0.044715f;
;   float u = x * __builtin_fmaf(x * x, c2, c1);
;   return x * __builtin_amdgcn_rcpf(1.0f + __builtin_amdgcn_exp2f(u));
; }
; template <int MODE>
; __device__ __forceinline__ void epi_elem(char* ws, float* outp, const float* b_gate, int g0, int rl, int col, f32x4 v) {
;   if (MODE == E_U || MODE == E_GV) {
;     int lc = col & 1023;
;     f32x4 o; for (int i = 0; i < 4; ++i) o[i] = gelu_f(v[i]);
;     u16* dst = (u16*)(ws + (MODE == E_U ? W_U : W_GV));
;     *(GAS uint2*)(dst + (size_t)rl * 1024 + lc) = pack4(o);
	v_mul_f32_e32 v172, v34, v172
	v_mul_f32_e32 v173, v35, v173
	v_mul_f32_e32 v174, v36, v174
	v_mul_f32_e32 v175, v37, v175
	v_exp_f32_e32 v168, v168
	v_exp_f32_e32 v169, v169
	v_exp_f32_e32 v170, v170
	v_exp_f32_e32 v171, v171
	v_exp_f32_e32 v172, v172
	v_exp_f32_e32 v173, v173
	v_exp_f32_e32 v174, v174
	v_exp_f32_e32 v175, v175
	v_add_f32_e32 v168, 1.0, v168
	v_add_f32_e32 v169, 1.0, v169
	v_add_f32_e32 v170, 1.0, v170
	v_add_f32_e32 v171, 1.0, v171
	v_add_f32_e32 v172, 1.0, v172
	v_add_f32_e32 v173, 1.0, v173
	v_add_f32_e32 v174, 1.0, v174
	v_add_f32_e32 v175, 1.0, v175
	v_rcp_f32_e32 v168, v168
	v_rcp_f32_e32 v169, v169
	v_rcp_f32_e32 v170, v170
	v_rcp_f32_e32 v171, v171
	v_rcp_f32_e32 v172, v172
	v_rcp_f32_e32 v173, v173
	v_rcp_f32_e32 v174, v174
	v_rcp_f32_e32 v175, v175
	v_mul_f32_e32 v168, v38, v168
	v_mul_f32_e32 v169, v39, v169
	v_mul_f32_e32 v170, v40, v170
	v_mul_f32_e32 v171, v41, v171
	v_mul_f32_e32 v172, v34, v172
	v_mul_f32_e32 v173, v35, v173
	v_mul_f32_e32 v174, v36, v174
	v_mul_f32_e32 v175, v37, v175
	v_cvt_pk_bf16_f32 v156, v168, v169
	v_cvt_pk_bf16_f32 v157, v170, v171
	v_cvt_pk_bf16_f32 v158, v172, v173
	v_cvt_pk_bf16_f32 v159, v174, v175
	v_permlane16_swap_b32_e32 v152, v154
	v_permlane16_swap_b32_e32 v153, v155
	global_store_dwordx4 v252, v[152:155], s[6:7]
	v_mul_f32_e32 v160, v30, v30
	v_mul_f32_e32 v161, v31, v31
	v_mul_f32_e32 v162, v32, v32
	v_mul_f32_e32 v163, v33, v33
	v_mul_f32_e32 v164, v26, v26
	v_mul_f32_e32 v165, v27, v27
	v_mul_f32_e32 v166, v28, v28
	v_mul_f32_e32 v167, v29, v29
	v_fma_f32 v160, v160, s18, v198
	v_fma_f32 v161, v161, s18, v198
	v_fma_f32 v162, v162, s18, v198
	v_fma_f32 v163, v163, s18, v198
	v_fma_f32 v164, v164, s18, v198
	v_fma_f32 v165, v165, s18, v198
	v_fma_f32 v166, v166, s18, v198
	v_fma_f32 v167, v167, s18, v198
	v_mul_f32_e32 v160, v30, v160
	v_mul_f32_e32 v161, v31, v161
	v_mul_f32_e32 v162, v32, v162
	v_mul_f32_e32 v163, v33, v163
	v_mul_f32_e32 v164, v26, v164
	v_mul_f32_e32 v165, v27, v165
	v_mul_f32_e32 v166, v28, v166
	v_mul_f32_e32 v167, v29, v167
	v_exp_f32_e32 v160, v160
	v_exp_f32_e32 v161, v161
	v_exp_f32_e32 v162, v162
	v_exp_f32_e32 v163, v163
	v_exp_f32_e32 v164, v164
	v_exp_f32_e32 v165, v165
	v_exp_f32_e32 v166, v166
	v_exp_f32_e32 v167, v167
	v_add_f32_e32 v160, 1.0, v160
	v_add_f32_e32 v161, 1.0, v161
	v_add_f32_e32 v162, 1.0, v162
	v_add_f32_e32 v163, 1.0, v163
	v_add_f32_e32 v164, 1.0, v164
	v_add_f32_e32 v165, 1.0, v165
	v_add_f32_e32 v166, 1.0, v166
	v_add_f32_e32 v167, 1.0, v167
	v_rcp_f32_e32 v160, v160
	v_rcp_f32_e32 v161, v161
	v_rcp_f32_e32 v162, v162
	v_rcp_f32_e32 v163, v163
	v_rcp_f32_e32 v164, v164
	v_rcp_f32_e32 v165, v165
	v_rcp_f32_e32 v166, v166
	v_rcp_f32_e32 v167, v167
	v_mul_f32_e32 v160, v30, v160
	v_mul_f32_e32 v161, v31, v161
	v_mul_f32_e32 v162, v32, v162
	v_mul_f32_e32 v163, v33, v163
	v_mul_f32_e32 v164, v26, v164
	v_mul_f32_e32 v165, v27, v165
	v_mul_f32_e32 v166, v28, v166
	v_mul_f32_e32 v167, v29, v167
	v_cvt_pk_bf16_f32 v144, v160, v161
	v_cvt_pk_bf16_f32 v145, v162, v163
	v_cvt_pk_bf16_f32 v146, v164, v165
	v_cvt_pk_bf16_f32 v147, v166, v167
	v_permlane16_swap_b32_e32 v156, v158
	v_permlane16_swap_b32_e32 v157, v159
	global_store_dwordx4 v253, v[156:159], s[6:7]
	v_mul_f32_e32 v168, v22, v22
	v_mul_f32_e32 v169, v23, v23
	v_mul_f32_e32 v170, v24, v24
	v_mul_f32_e32 v171, v25, v25
	v_mul_f32_e32 v172, v18, v18
	v_mul_f32_e32 v173, v19, v19
	v_mul_f32_e32 v174, v20, v20
	v_mul_f32_e32 v175, v21, v21
	v_fma_f32 v168, v168, s18, v198
	v_fma_f32 v169, v169, s18, v198
	v_fma_f32 v170, v170, s18, v198
	v_fma_f32 v171, v171, s18, v198
	v_fma_f32 v172, v172, s18, v198
	v_fma_f32 v173, v173, s18, v198
	v_fma_f32 v174, v174, s18, v198
	v_fma_f32 v175, v175, s18, v198
	v_mul_f32_e32 v168, v22, v168
	v_mul_f32_e32 v169, v23, v169
	v_mul_f32_e32 v170, v24, v170
	v_mul_f32_e32 v171, v25, v171
	v_mul_f32_e32 v172, v18, v172
	v_mul_f32_e32 v173, v19, v173
	v_mul_f32_e32 v174, v20, v174
	v_mul_f32_e32 v175, v21, v175
	v_exp_f32_e32 v168, v168
	v_exp_f32_e32 v169, v169
	v_exp_f32_e32 v170, v170
	v_exp_f32_e32 v171, v171
	v_exp_f32_e32 v172, v172
	v_exp_f32_e32 v173, v173
	v_exp_f32_e32 v174, v174
	v_exp_f32_e32 v175, v175
	v_add_f32_e32 v168, 1.0, v168
	v_add_f32_e32 v169, 1.0, v169
	v_add_f32_e32 v170, 1.0, v170
	v_add_f32_e32 v171, 1.0, v171
	v_add_f32_e32 v172, 1.0, v172
	v_add_f32_e32 v173, 1.0, v173
	v_add_f32_e32 v174, 1.0, v174
	v_add_f32_e32 v175, 1.0, v175
	v_rcp_f32_e32 v168, v168
	v_rcp_f32_e32 v169, v169
	v_rcp_f32_e32 v170, v170
	v_rcp_f32_e32 v171, v171
	v_rcp_f32_e32 v172, v172
	v_rcp_f32_e32 v173, v173
	v_rcp_f32_e32 v174, v174
	v_rcp_f32_e32 v175, v175
	v_mul_f32_e32 v168, v22, v168
; #define GAS __attribute__((address_space(1)))
; __device__ __forceinline__ uint2 pack4(f32x4 v) { return make_uint2(pack2(v[0], v[1]), pack2(v[2], v[3])); }
; __device__ __forceinline__ float gelu_f(float x) {
;   const float c1 = -1.5957691216057308f * 1.4426950408889634f, c2 = c1 * 0.044715f;
;   float u = x * __builtin_fmaf(x * x, c2, c1);
;   return x * __builtin_amdgcn_rcpf(1.0f + __builtin_amdgcn_exp2f(u));
; }
; template <int MODE>
; __device__ __forceinline__ void epi_elem(char* ws, float* outp, const float* b_gate, int g0, int rl, int col, f32x4 v) {
;   if (MODE == E_U || MODE == E_GV) {
;     int lc = col & 1023;
;     f32x4 o; for (int i = 0; i < 4; ++i) o[i] = gelu_f(v[i]);
;     u16* dst = (u16*)(ws + (MODE == E_U ? W_U : W_GV));
;     *(GAS uint2*)(dst + (size_t)rl * 1024 + lc) = pack4(o);
	v_mul_f32_e32 v169, v23, v169
	v_mul_f32_e32 v170, v24, v170
	v_mul_f32_e32 v171, v25, v171
	v_mul_f32_e32 v172, v18, v172
	v_mul_f32_e32 v173, v19, v173
	v_mul_f32_e32 v174, v20, v174
	v_mul_f32_e32 v175, v21, v175
	v_cvt_pk_bf16_f32 v148, v168, v169
	v_cvt_pk_bf16_f32 v149, v170, v171
	v_cvt_pk_bf16_f32 v150, v172, v173
	v_cvt_pk_bf16_f32 v151, v174, v175
	v_permlane16_swap_b32_e32 v144, v146
	v_permlane16_swap_b32_e32 v145, v147
	global_store_dwordx4 v250, v[144:147], s[6:7] offset:256
	v_mul_f32_e32 v160, v14, v14
	v_mul_f32_e32 v161, v15, v15
	v_mul_f32_e32 v162, v16, v16
	v_mul_f32_e32 v163, v17, v17
	v_mul_f32_e32 v164, v10, v10
	v_mul_f32_e32 v165, v11, v11
	v_mul_f32_e32 v166, v12, v12
	v_mul_f32_e32 v167, v13, v13
	v_fma_f32 v160, v160, s18, v198
	v_fma_f32 v161, v161, s18, v198
	v_fma_f32 v162, v162, s18, v198
	v_fma_f32 v163, v163, s18, v198
	v_fma_f32 v164, v164, s18, v198
	v_fma_f32 v165, v165, s18, v198
	v_fma_f32 v166, v166, s18, v198
	v_fma_f32 v167, v167, s18, v198
	v_mul_f32_e32 v160, v14, v160
	v_mul_f32_e32 v161, v15, v161
	v_mul_f32_e32 v162, v16, v162
	v_mul_f32_e32 v163, v17, v163
	v_mul_f32_e32 v164, v10, v164
	v_mul_f32_e32 v165, v11, v165
	v_mul_f32_e32 v166, v12, v166
	v_mul_f32_e32 v167, v13, v167
	v_exp_f32_e32 v160, v160
	v_exp_f32_e32 v161, v161
	v_exp_f32_e32 v162, v162
	v_exp_f32_e32 v163, v163
	v_exp_f32_e32 v164, v164
	v_exp_f32_e32 v165, v165
	v_exp_f32_e32 v166, v166
	v_exp_f32_e32 v167, v167
	v_add_f32_e32 v160, 1.0, v160
	v_add_f32_e32 v161, 1.0, v161
	v_add_f32_e32 v162, 1.0, v162
	v_add_f32_e32 v163, 1.0, v163
	v_add_f32_e32 v164, 1.0, v164
	v_add_f32_e32 v165, 1.0, v165
	v_add_f32_e32 v166, 1.0, v166
	v_add_f32_e32 v167, 1.0, v167
	v_rcp_f32_e32 v160, v160
	v_rcp_f32_e32 v161, v161
	v_rcp_f32_e32 v162, v162
	v_rcp_f32_e32 v163, v163
	v_rcp_f32_e32 v164, v164
	v_rcp_f32_e32 v165, v165
	v_rcp_f32_e32 v166, v166
	v_rcp_f32_e32 v167, v167
	v_mul_f32_e32 v160, v14, v160
	v_mul_f32_e32 v161, v15, v161
	v_mul_f32_e32 v162, v16, v162
	v_mul_f32_e32 v163, v17, v163
	v_mul_f32_e32 v164, v10, v164
	v_mul_f32_e32 v165, v11, v165
	v_mul_f32_e32 v166, v12, v166
	v_mul_f32_e32 v167, v13, v167
	v_cvt_pk_bf16_f32 v152, v160, v161
	v_cvt_pk_bf16_f32 v153, v162, v163
	v_cvt_pk_bf16_f32 v154, v164, v165
	v_cvt_pk_bf16_f32 v155, v166, v167
	v_permlane16_swap_b32_e32 v148, v150
	v_permlane16_swap_b32_e32 v149, v151
	global_store_dwordx4 v251, v[148:151], s[6:7] offset:256
	v_mul_f32_e32 v168, v6, v6
	v_mul_f32_e32 v169, v7, v7
	v_mul_f32_e32 v170, v8, v8
	v_mul_f32_e32 v171, v9, v9
	v_mul_f32_e32 v172, v2, v2
	v_mul_f32_e32 v173, v3, v3
	v_mul_f32_e32 v174, v4, v4
	v_mul_f32_e32 v175, v5, v5
	v_fma_f32 v168, v168, s18, v198
	v_fma_f32 v169, v169, s18, v198
	v_fma_f32 v170, v170, s18, v198
	v_fma_f32 v171, v171, s18, v198
	v_fma_f32 v172, v172, s18, v198
	v_fma_f32 v173, v173, s18, v198
	v_fma_f32 v174, v174, s18, v198
	v_fma_f32 v175, v175, s18, v198
	v_mul_f32_e32 v168, v6, v168
	v_mul_f32_e32 v169, v7, v169
	v_mul_f32_e32 v170, v8, v170
	v_mul_f32_e32 v171, v9, v171
	v_mul_f32_e32 v172, v2, v172
	v_mul_f32_e32 v173, v3, v173
	v_mul_f32_e32 v174, v4, v174
	v_mul_f32_e32 v175, v5, v175
	v_exp_f32_e32 v168, v168
	v_exp_f32_e32 v169, v169
	v_exp_f32_e32 v170, v170
	v_exp_f32_e32 v171, v171
	v_exp_f32_e32 v172, v172
	v_exp_f32_e32 v173, v173
	v_exp_f32_e32 v174, v174
	v_exp_f32_e32 v175, v175
	v_add_f32_e32 v168, 1.0, v168
	v_add_f32_e32 v169, 1.0, v169
	v_add_f32_e32 v170, 1.0, v170
	v_add_f32_e32 v171, 1.0, v171
	v_add_f32_e32 v172, 1.0, v172
	v_add_f32_e32 v173, 1.0, v173
	v_add_f32_e32 v174, 1.0, v174
	v_add_f32_e32 v175, 1.0, v175
	v_rcp_f32_e32 v168, v168
	v_rcp_f32_e32 v169, v169
	v_rcp_f32_e32 v170, v170
	v_rcp_f32_e32 v171, v171
	v_rcp_f32_e32 v172, v172
	v_rcp_f32_e32 v173, v173
	v_rcp_f32_e32 v174, v174
	v_rcp_f32_e32 v175, v175
	v_mul_f32_e32 v168, v6, v168
	v_mul_f32_e32 v169, v7, v169
	v_mul_f32_e32 v170, v8, v170
	v_mul_f32_e32 v171, v9, v171
	v_mul_f32_e32 v172, v2, v172
	v_mul_f32_e32 v173, v3, v173
	v_mul_f32_e32 v174, v4, v174
	v_mul_f32_e32 v175, v5, v175
	v_cvt_pk_bf16_f32 v156, v168, v169
	v_cvt_pk_bf16_f32 v157, v170, v171
	v_cvt_pk_bf16_f32 v158, v172, v173
	v_cvt_pk_bf16_f32 v159, v174, v175
	v_permlane16_swap_b32_e32 v152, v154
	v_permlane16_swap_b32_e32 v153, v155
	global_store_dwordx4 v252, v[152:155], s[6:7] offset:256
	s_nop 1
	v_permlane16_swap_b32_e32 v156, v158
	v_permlane16_swap_b32_e32 v157, v159
	global_store_dwordx4 v253, v[156:159], s[6:7] offset:256
	s_branch .LBB0_619
.LBB0_619:
	s_xor_b64 s[2:3], s[54:55], -1
	s_and_b64 s[2:3], s[2:3], s[48:49]
	s_and_b64 s[4:5], s[54:55], exec
	s_cselect_b32 s8, 0, 35
	s_mov_b64 s[6:7], 0
